# non-temporal hint also on weight loads of the prep phases, residual loads of the output-projection epilogue, Q and gate loads of the attention units
# baseline (speedup 1.0000x reference)
.LBB0_27:
	s_andn2_b64 vcc, exec, s[0:1]
	s_cbranch_vccnz .LBB0_36
	s_barrier
	s_and_saveexec_b64 s[0:1], s[4:5]
	ds_write_b32 v26, v5 offset:40960
	s_or_b64 exec, exec, s[0:1]
	s_add_i32 s0, s74, 0xfffffa80
	s_lshr_b32 s25, s0, 6
	s_lshl_b32 s0, s74, 6
	s_and_b32 s24, s0, 0xc0
	s_lshl_b32 s0, s74, 4
	s_and_b32 s22, s0, 0x3c0
	v_or_b32_e32 v2, s22, v28
	v_mul_u32_u24_e32 v2, 0x13a0, v2
	v_mad_u64_u32 v[10:11], s[0:1], s25, v58, v[6:7]
	v_add_lshl_u32 v2, v2, s24, 2
	v_lshl_add_u64 v[12:13], v[10:11], 0, v[2:3]
	v_or_b32_e32 v2, s22, v31
	v_mul_u32_u24_e32 v2, 0x13a0, v2
	v_add_lshl_u32 v2, v2, s24, 2
	v_lshl_add_u64 v[14:15], v[10:11], 0, v[2:3]
	v_or_b32_e32 v2, s22, v32
	v_mul_u32_u24_e32 v2, 0x13a0, v2
	v_add_lshl_u32 v2, v2, s24, 2
	v_lshl_add_u64 v[16:17], v[10:11], 0, v[2:3]
	v_or_b32_e32 v2, s22, v33
	v_mul_u32_u24_e32 v2, 0x13a0, v2
	v_add_lshl_u32 v2, v2, s24, 2
	v_lshl_add_u64 v[18:19], v[10:11], 0, v[2:3]
	v_or_b32_e32 v2, s22, v34
	v_mul_u32_u24_e32 v2, 0x13a0, v2
	v_add_lshl_u32 v2, v2, s24, 2
	v_lshl_add_u64 v[20:21], v[10:11], 0, v[2:3]
	v_or_b32_e32 v2, s22, v36
	v_mul_u32_u24_e32 v2, 0x13a0, v2
	v_add_lshl_u32 v2, v2, s24, 2
	v_lshl_add_u64 v[22:23], v[10:11], 0, v[2:3]
	v_or_b32_e32 v2, s22, v37
	v_mul_u32_u24_e32 v2, 0x13a0, v2
	v_add_lshl_u32 v2, v2, s24, 2
	v_lshl_add_u64 v[24:25], v[10:11], 0, v[2:3]
	v_or_b32_e32 v2, s22, v39
	v_mul_u32_u24_e32 v2, 0x13a0, v2
	v_add_lshl_u32 v2, v2, s24, 2
	v_lshl_add_u64 v[64:65], v[10:11], 0, v[2:3]
	v_or_b32_e32 v2, s22, v40
	v_mul_u32_u24_e32 v2, 0x13a0, v2
	v_add_lshl_u32 v2, v2, s24, 2
	global_load_dword v59, v[12:13], off nt
	global_load_dword v66, v[14:15], off nt
	global_load_dword v67, v[16:17], off nt
	global_load_dword v68, v[18:19], off nt
	global_load_dword v69, v[20:21], off nt
	global_load_dword v70, v[22:23], off nt
	global_load_dword v71, v[24:25], off nt
	s_nop 0
	global_load_dword v64, v[64:65], off nt
	v_lshl_add_u64 v[12:13], v[10:11], 0, v[2:3]
	v_or_b32_e32 v2, s22, v41
	v_mul_u32_u24_e32 v2, 0x13a0, v2
	v_add_lshl_u32 v2, v2, s24, 2
	v_lshl_add_u64 v[14:15], v[10:11], 0, v[2:3]
	v_or_b32_e32 v2, s22, v42
	v_mul_u32_u24_e32 v2, 0x13a0, v2
	v_add_lshl_u32 v2, v2, s24, 2
	v_lshl_add_u64 v[16:17], v[10:11], 0, v[2:3]
	v_or_b32_e32 v2, s22, v43
	v_mul_u32_u24_e32 v2, 0x13a0, v2
	v_add_lshl_u32 v2, v2, s24, 2
	v_lshl_add_u64 v[18:19], v[10:11], 0, v[2:3]
	v_or_b32_e32 v2, s22, v44
	v_mul_u32_u24_e32 v2, 0x13a0, v2
	v_add_lshl_u32 v2, v2, s24, 2
	v_lshl_add_u64 v[20:21], v[10:11], 0, v[2:3]
	v_or_b32_e32 v2, s22, v45
	v_mul_u32_u24_e32 v2, 0x13a0, v2
	v_add_lshl_u32 v2, v2, s24, 2
	v_lshl_add_u64 v[22:23], v[10:11], 0, v[2:3]
	v_or_b32_e32 v2, s22, v46
	v_mul_u32_u24_e32 v2, 0x13a0, v2
	v_add_lshl_u32 v2, v2, s24, 2
	v_lshl_add_u64 v[24:25], v[10:11], 0, v[2:3]
	v_or_b32_e32 v2, s22, v47
	v_mul_u32_u24_e32 v2, 0x13a0, v2
	v_add_lshl_u32 v2, v2, s24, 2
	v_lshl_add_u64 v[10:11], v[10:11], 0, v[2:3]
	global_load_dword v2, v[12:13], off nt
	s_nop 0
	global_load_dword v12, v[14:15], off nt
	global_load_dword v13, v[16:17], off nt
	s_nop 0
	global_load_dword v14, v[18:19], off nt
	global_load_dword v15, v[20:21], off nt
	global_load_dword v16, v[22:23], off nt
	global_load_dword v17, v[24:25], off nt
	s_nop 0
	global_load_dword v10, v[10:11], off nt
	v_add_u32_e32 v11, v29, v30
	s_waitcnt vmcnt(15)
	ds_write_b32 v11, v59
	s_waitcnt vmcnt(14)
	ds_write_b32 v11, v66 offset:1040
	s_waitcnt vmcnt(13)
	ds_write_b32 v11, v67 offset:2080
	s_waitcnt vmcnt(12)
	ds_write_b32 v11, v68 offset:3120
	s_waitcnt vmcnt(11)
	ds_write_b32 v11, v69 offset:4160
	s_waitcnt vmcnt(10)
	ds_write_b32 v11, v70 offset:5200
	v_add_u32_e32 v11, v29, v38
	s_waitcnt vmcnt(9)
	ds_write_b32 v11, v71
	s_waitcnt vmcnt(8)
	ds_write_b32 v11, v64 offset:1040
	s_waitcnt vmcnt(7)
	ds_write_b32 v11, v2 offset:2080
	s_waitcnt vmcnt(6)
	ds_write_b32 v11, v12 offset:3120
	s_waitcnt vmcnt(5)
	ds_write_b32 v11, v13 offset:4160
	s_waitcnt vmcnt(4)
	ds_write_b32 v11, v14 offset:5200
	s_waitcnt vmcnt(3)
	ds_write_b32 v11, v15 offset:6240
	s_waitcnt vmcnt(2)
	ds_write_b32 v11, v16 offset:7280
	s_waitcnt vmcnt(1)
	ds_write_b32 v11, v17 offset:8320
	s_waitcnt vmcnt(0)
	ds_write_b32 v11, v10 offset:9360
	s_waitcnt lgkmcnt(0)
	s_barrier
	s_and_saveexec_b64 s[0:1], s[20:21]
	s_xor_b64 s[0:1], exec, s[0:1]
	s_cbranch_execz .LBB0_33
	v_mov_b32_e32 v10, 0
	s_mov_b32 s44, 0
	v_mov_b32_e32 v2, v50
	v_mov_b32_e32 v11, v10
	v_mov_b32_e32 v20, v10
	v_mov_b32_e32 v21, v10
	v_mov_b32_e32 v24, v10
	v_mov_b32_e32 v25, v10
	v_mov_b32_e32 v22, v10
	v_mov_b32_e32 v23, v10
	v_mov_b32_e32 v14, v10
	v_mov_b32_e32 v15, v10
	v_mov_b32_e32 v12, v10
	v_mov_b32_e32 v13, v10
	v_mov_b32_e32 v18, v10
	v_mov_b32_e32 v19, v10
	v_mov_b32_e32 v16, v10
	v_mov_b32_e32 v17, v10

.LBB0_42:
	s_or_saveexec_b64 s[44:45], s[44:45]
	v_ashrrev_i32_e32 v11, 31, v10
	s_lshl_b32 s22, s22, 6
	v_lshl_add_u64 v[10:11], v[10:11], 2, s[46:47]
	v_mov_b32_e32 v2, 0
	v_mov_b32_e32 v13, 0
	v_mov_b32_e32 v14, 0
	v_mov_b32_e32 v15, 0
	s_xor_b64 exec, exec, s[44:45]
	s_cbranch_execz .LBB0_44
	v_or_b32_e32 v2, s22, v28
	v_mul_lo_u32 v2, v2, s55
	v_lshl_add_u64 v[14:15], v[2:3], 2, v[10:11]
	v_or_b32_e32 v2, s22, v31
	v_add_co_u32_e32 v14, vcc, 0x1000, v14
	v_mul_lo_u32 v2, v2, s55
	s_nop 0
	v_addc_co_u32_e32 v15, vcc, 0, v15, vcc
	v_lshl_add_u64 v[16:17], v[2:3], 2, v[10:11]
	v_or_b32_e32 v2, s22, v32
	v_add_co_u32_e32 v16, vcc, 0x1000, v16
	v_mul_lo_u32 v2, v2, s55
	s_nop 0
	v_addc_co_u32_e32 v17, vcc, 0, v17, vcc
	v_lshl_add_u64 v[18:19], v[2:3], 2, v[10:11]
	v_or_b32_e32 v2, s22, v33
	v_add_co_u32_e32 v18, vcc, 0x1000, v18
	v_mul_lo_u32 v2, v2, s55
	s_nop 0
	v_addc_co_u32_e32 v19, vcc, 0, v19, vcc
	v_lshl_add_u64 v[20:21], v[2:3], 2, v[10:11]
	v_or_b32_e32 v2, s22, v34
	v_add_co_u32_e32 v20, vcc, 0x1000, v20
	v_mul_lo_u32 v2, v2, s55
	s_nop 0
	v_addc_co_u32_e32 v21, vcc, 0, v21, vcc
	v_lshl_add_u64 v[22:23], v[2:3], 2, v[10:11]
	v_or_b32_e32 v2, s22, v36
	v_add_co_u32_e32 v22, vcc, 0x1000, v22
	v_mul_lo_u32 v2, v2, s55
	s_nop 0
	v_addc_co_u32_e32 v23, vcc, 0, v23, vcc
	v_lshl_add_u64 v[24:25], v[2:3], 2, v[10:11]
	v_or_b32_e32 v2, s22, v37
	v_add_co_u32_e32 v24, vcc, 0x1000, v24
	v_mul_lo_u32 v2, v2, s55
	s_nop 0
	v_addc_co_u32_e32 v25, vcc, 0, v25, vcc
	v_lshl_add_u64 v[64:65], v[2:3], 2, v[10:11]
	v_or_b32_e32 v2, s22, v39
	v_add_co_u32_e32 v64, vcc, 0x1000, v64
	v_mul_lo_u32 v2, v2, s55
	s_nop 0
	v_addc_co_u32_e32 v65, vcc, 0, v65, vcc
	v_lshl_add_u64 v[66:67], v[2:3], 2, v[10:11]
	v_add_co_u32_e32 v66, vcc, 0x1000, v66
	s_nop 1
	v_addc_co_u32_e32 v67, vcc, 0, v67, vcc
	global_load_dword v59, v[14:15], off offset:3712 nt
	s_nop 0
	global_load_dword v16, v[16:17], off offset:3712 nt
	s_nop 0
	global_load_dword v17, v[18:19], off offset:3712 nt
	s_nop 0
	global_load_dword v18, v[20:21], off offset:3712 nt
	global_load_dword v2, v[22:23], off offset:3712 nt
	global_load_dword v13, v[24:25], off offset:3712 nt
	global_load_dword v14, v[64:65], off offset:3712 nt
	global_load_dword v15, v[66:67], off offset:3712 nt
	v_add_u32_e32 v19, v29, v30
	s_waitcnt vmcnt(7)
	ds_write_b32 v19, v59
	s_waitcnt vmcnt(6)
	ds_write_b32 v19, v16 offset:1040
	s_waitcnt vmcnt(5)
	ds_write_b32 v19, v17 offset:2080
	s_waitcnt vmcnt(4)
	ds_write_b32 v19, v18 offset:3120

.LBB0_46:
	s_or_saveexec_b64 s[0:1], s[0:1]
	v_mov_b32_e32 v2, 0
	v_mov_b32_e32 v13, 0
	v_mov_b32_e32 v14, 0
	v_mov_b32_e32 v15, 0
	s_xor_b64 exec, exec, s[0:1]
	s_cbranch_execz .LBB0_48
	v_or_b32_e32 v2, s22, v40
	v_mul_lo_u32 v2, v2, s55
	v_lshl_add_u64 v[14:15], v[2:3], 2, v[10:11]
	v_or_b32_e32 v2, s22, v41
	v_add_co_u32_e32 v14, vcc, 0x1000, v14
	v_mul_lo_u32 v2, v2, s55
	s_nop 0
	v_addc_co_u32_e32 v15, vcc, 0, v15, vcc
	v_lshl_add_u64 v[16:17], v[2:3], 2, v[10:11]
	v_or_b32_e32 v2, s22, v42
	v_add_co_u32_e32 v16, vcc, 0x1000, v16
	v_mul_lo_u32 v2, v2, s55
	s_nop 0
	v_addc_co_u32_e32 v17, vcc, 0, v17, vcc
	v_lshl_add_u64 v[18:19], v[2:3], 2, v[10:11]
	v_or_b32_e32 v2, s22, v43
	v_add_co_u32_e32 v18, vcc, 0x1000, v18
	v_mul_lo_u32 v2, v2, s55
	s_nop 0
	v_addc_co_u32_e32 v19, vcc, 0, v19, vcc
	v_lshl_add_u64 v[20:21], v[2:3], 2, v[10:11]
	v_or_b32_e32 v2, s22, v44
	v_add_co_u32_e32 v20, vcc, 0x1000, v20
	v_mul_lo_u32 v2, v2, s55
	s_nop 0
	v_addc_co_u32_e32 v21, vcc, 0, v21, vcc
	v_lshl_add_u64 v[22:23], v[2:3], 2, v[10:11]
	v_or_b32_e32 v2, s22, v45
	v_add_co_u32_e32 v22, vcc, 0x1000, v22
	v_mul_lo_u32 v2, v2, s55
	s_nop 0
	v_addc_co_u32_e32 v23, vcc, 0, v23, vcc
	v_lshl_add_u64 v[24:25], v[2:3], 2, v[10:11]
	v_or_b32_e32 v2, s22, v46
	v_add_co_u32_e32 v24, vcc, 0x1000, v24
	v_mul_lo_u32 v2, v2, s55
	s_nop 0
	v_addc_co_u32_e32 v25, vcc, 0, v25, vcc
	v_lshl_add_u64 v[64:65], v[2:3], 2, v[10:11]
	v_or_b32_e32 v2, s22, v47
	v_add_co_u32_e32 v64, vcc, 0x1000, v64
	v_mul_lo_u32 v2, v2, s55
	s_nop 0
	v_addc_co_u32_e32 v65, vcc, 0, v65, vcc
	v_lshl_add_u64 v[10:11], v[2:3], 2, v[10:11]
	v_add_co_u32_e32 v10, vcc, 0x1000, v10
	s_nop 1
	v_addc_co_u32_e32 v11, vcc, 0, v11, vcc
	global_load_dword v59, v[14:15], off offset:3712 nt
	s_nop 0
	global_load_dword v16, v[16:17], off offset:3712 nt
	s_nop 0
	global_load_dword v17, v[18:19], off offset:3712 nt
	s_nop 0
	global_load_dword v18, v[20:21], off offset:3712 nt
	global_load_dword v2, v[22:23], off offset:3712 nt
	global_load_dword v13, v[24:25], off offset:3712 nt
	global_load_dword v14, v[64:65], off offset:3712 nt
	global_load_dword v15, v[10:11], off offset:3712 nt
	v_add_u32_e32 v10, v29, v38
	s_waitcnt vmcnt(7)
	ds_write_b32 v10, v59 offset:2080
	s_waitcnt vmcnt(6)
	ds_write_b32 v10, v16 offset:3120
	s_waitcnt vmcnt(5)
	ds_write_b32 v10, v17 offset:4160
	s_waitcnt vmcnt(4)
	ds_write_b32 v10, v18 offset:5200

.LBB0_57:
	s_or_saveexec_b64 s[24:25], s[24:25]
	v_ashrrev_i32_e32 v11, 31, v10
	s_lshl_b32 s22, s22, 6
	v_lshl_add_u64 v[10:11], v[10:11], 2, s[44:45]
	v_mov_b32_e32 v2, 0
	v_mov_b32_e32 v13, 0
	v_mov_b32_e32 v14, 0
	v_mov_b32_e32 v15, 0
	s_xor_b64 exec, exec, s[24:25]
	s_cbranch_execz .LBB0_59
	v_or_b32_e32 v2, s22, v28
	v_mul_lo_u32 v2, v2, s55
	v_lshl_add_u64 v[14:15], v[2:3], 2, v[10:11]
	v_or_b32_e32 v2, s22, v31
	v_mul_lo_u32 v2, v2, s55
	v_lshl_add_u64 v[16:17], v[2:3], 2, v[10:11]
	v_or_b32_e32 v2, s22, v32
	v_mul_lo_u32 v2, v2, s55
	v_lshl_add_u64 v[18:19], v[2:3], 2, v[10:11]
	v_or_b32_e32 v2, s22, v33
	v_mul_lo_u32 v2, v2, s55
	v_lshl_add_u64 v[20:21], v[2:3], 2, v[10:11]
	v_or_b32_e32 v2, s22, v34
	v_mul_lo_u32 v2, v2, s55
	v_lshl_add_u64 v[22:23], v[2:3], 2, v[10:11]
	v_or_b32_e32 v2, s22, v36
	v_mul_lo_u32 v2, v2, s55
	v_lshl_add_u64 v[24:25], v[2:3], 2, v[10:11]
	v_or_b32_e32 v2, s22, v37
	v_mul_lo_u32 v2, v2, s55
	v_lshl_add_u64 v[64:65], v[2:3], 2, v[10:11]
	v_or_b32_e32 v2, s22, v39
	v_mul_lo_u32 v2, v2, s55
	v_lshl_add_u64 v[66:67], v[2:3], 2, v[10:11]
	global_load_dword v59, v[14:15], off offset:1024 nt
	s_nop 0
	global_load_dword v16, v[16:17], off offset:1024 nt
	s_nop 0
	global_load_dword v17, v[18:19], off offset:1024 nt
	s_nop 0
	global_load_dword v18, v[20:21], off offset:1024 nt
	global_load_dword v2, v[22:23], off offset:1024 nt
	global_load_dword v13, v[24:25], off offset:1024 nt
	global_load_dword v14, v[64:65], off offset:1024 nt
	global_load_dword v15, v[66:67], off offset:1024 nt
	v_add_u32_e32 v19, v29, v30
	s_waitcnt vmcnt(7)
	ds_write_b32 v19, v59
	s_waitcnt vmcnt(6)
	ds_write_b32 v19, v16 offset:1040
	s_waitcnt vmcnt(5)
	ds_write_b32 v19, v17 offset:2080
	s_waitcnt vmcnt(4)
	ds_write_b32 v19, v18 offset:3120

.LBB0_61:
	s_or_saveexec_b64 s[24:25], s[24:25]
	v_mov_b32_e32 v2, 0
	v_mov_b32_e32 v14, 0
	v_mov_b32_e32 v15, 0
	v_mov_b32_e32 v16, 0
	s_xor_b64 exec, exec, s[24:25]
	s_cbranch_execz .LBB0_63
	v_or_b32_e32 v2, s22, v40
	v_mul_lo_u32 v2, v2, s55
	v_lshl_add_u64 v[14:15], v[2:3], 2, v[10:11]
	v_or_b32_e32 v2, s22, v41
	v_mul_lo_u32 v2, v2, s55
	v_lshl_add_u64 v[16:17], v[2:3], 2, v[10:11]
	v_or_b32_e32 v2, s22, v42
	v_mul_lo_u32 v2, v2, s55
	v_lshl_add_u64 v[18:19], v[2:3], 2, v[10:11]
	v_or_b32_e32 v2, s22, v43
	v_mul_lo_u32 v2, v2, s55
	v_lshl_add_u64 v[20:21], v[2:3], 2, v[10:11]
	v_or_b32_e32 v2, s22, v44
	v_mul_lo_u32 v2, v2, s55
	v_lshl_add_u64 v[22:23], v[2:3], 2, v[10:11]
	v_or_b32_e32 v2, s22, v45
	v_mul_lo_u32 v2, v2, s55
	v_lshl_add_u64 v[24:25], v[2:3], 2, v[10:11]
	v_or_b32_e32 v2, s22, v46
	v_mul_lo_u32 v2, v2, s55
	v_lshl_add_u64 v[64:65], v[2:3], 2, v[10:11]
	v_or_b32_e32 v2, s22, v47
	v_mul_lo_u32 v2, v2, s55
	v_lshl_add_u64 v[10:11], v[2:3], 2, v[10:11]
	global_load_dword v59, v[14:15], off offset:1024 nt
	s_nop 0
	global_load_dword v17, v[16:17], off offset:1024 nt
	s_nop 0
	global_load_dword v18, v[18:19], off offset:1024 nt
	s_nop 0
	global_load_dword v19, v[20:21], off offset:1024 nt
	global_load_dword v2, v[22:23], off offset:1024 nt
	global_load_dword v14, v[24:25], off offset:1024 nt
	global_load_dword v15, v[64:65], off offset:1024 nt
	global_load_dword v16, v[10:11], off offset:1024 nt
	s_waitcnt vmcnt(7)
	ds_write_b32 v13, v59 offset:2080
	s_waitcnt vmcnt(6)
	ds_write_b32 v13, v17 offset:3120
	s_waitcnt vmcnt(5)
	ds_write_b32 v13, v18 offset:4160
	s_waitcnt vmcnt(4)
	ds_write_b32 v13, v19 offset:5200

.LBB0_68:
	s_mul_hi_i32 s0, s74, 0x2aaaaaab
	s_lshr_b32 s1, s0, 31
	s_ashr_i32 s0, s0, 4
	s_add_i32 s0, s0, s1
	s_mul_i32 s1, s0, 0x60
	s_sub_i32 s22, s74, s1
	s_bfe_i32 s1, s22, 0x80000
	s_bfe_u32 s1, s1, 0x4000b
	s_add_i32 s1, s22, s1
	s_and_b32 s24, s1, 0xf0
	s_sub_i32 s22, s22, s24
	s_sext_i32_i8 s22, s22
	s_lshl_b32 s44, s22, 6
	s_barrier
	s_and_saveexec_b64 s[24:25], s[6:7]
	s_cbranch_execz .LBB0_70
	v_add_u32_e32 v2, s44, v56
	v_or_b32_e32 v10, s44, v0
	v_cndmask_b32_e64 v10, v2, v10, s[8:9]
	v_ashrrev_i32_e32 v11, 31, v10
	v_lshl_add_u64 v[10:11], v[10:11], 2, v[8:9]
	global_load_dword v2, v[10:11], off nt
	s_waitcnt vmcnt(0)
	v_mul_f32_e32 v10, 0xbfb8aa3b, v2
	v_exp_f32_e32 v10, v10
	s_nop 0
	v_add_f32_e32 v10, 1.0, v10
	v_rcp_f32_e32 v10, v10
	s_nop 0
	v_mul_f32_e32 v2, v2, v10
	ds_write_b32 v26, v2

.LBB0_71:
	v_lshl_add_u64 v[18:19], v[12:13], 0, s[24:25]
	v_add_co_u32_e32 v20, vcc, s53, v18
	global_load_dword v2, v[18:19], off nt
	s_nop 0
	v_addc_co_u32_e32 v21, vcc, 0, v19, vcc
	v_add_co_u32_e32 v22, vcc, s60, v18
	v_mov_b32_e32 v17, s1
	s_nop 0
	v_addc_co_u32_e32 v23, vcc, 0, v19, vcc
	v_add_co_u32_e32 v24, vcc, s61, v18
	s_add_u32 s24, s24, 0x30000
	s_nop 0
	v_addc_co_u32_e32 v25, vcc, 0, v19, vcc
	v_add_co_u32_e32 v64, vcc, s62, v18
	s_addc_u32 s25, s25, 0
	s_nop 0
	v_addc_co_u32_e32 v65, vcc, 0, v19, vcc
	v_add_co_u32_e32 v66, vcc, s63, v18
	s_add_i32 s1, s1, 64
	s_nop 0
	v_addc_co_u32_e32 v67, vcc, 0, v19, vcc
	v_add_co_u32_e32 v68, vcc, s64, v18
	s_cmp_eq_u32 s24, 0xc0000
	s_nop 0
	v_addc_co_u32_e32 v69, vcc, 0, v19, vcc
	v_add_co_u32_e32 v70, vcc, s65, v18
	s_nop 1
	v_addc_co_u32_e32 v71, vcc, 0, v19, vcc
	v_add_co_u32_e32 v72, vcc, s66, v18
	s_nop 1
	v_addc_co_u32_e32 v73, vcc, 0, v19, vcc
	v_add_co_u32_e32 v74, vcc, s67, v18
	s_nop 1
	v_addc_co_u32_e32 v75, vcc, 0, v19, vcc
	v_add_co_u32_e32 v76, vcc, s68, v18
	s_nop 1
	v_addc_co_u32_e32 v77, vcc, 0, v19, vcc
	v_add_co_u32_e32 v78, vcc, s69, v18
	s_nop 1
	v_addc_co_u32_e32 v79, vcc, 0, v19, vcc
	v_add_co_u32_e32 v80, vcc, s70, v18
	s_nop 1
	v_addc_co_u32_e32 v81, vcc, 0, v19, vcc
	v_add_co_u32_e32 v82, vcc, s71, v18
	s_nop 1
	v_addc_co_u32_e32 v83, vcc, 0, v19, vcc
	v_add_co_u32_e32 v84, vcc, s72, v18
	s_nop 1
	v_addc_co_u32_e32 v85, vcc, 0, v19, vcc
	v_add_co_u32_e32 v18, vcc, s73, v18
	s_nop 1
	v_addc_co_u32_e32 v19, vcc, 0, v19, vcc
	global_load_dword v104, v[20:21], off nt
	global_load_dword v106, v[22:23], off nt
	global_load_dword v108, v[24:25], off nt
	global_load_dword v110, v[64:65], off nt
	global_load_dword v112, v[66:67], off nt
	global_load_dword v114, v[68:69], off nt
	global_load_dword v116, v[70:71], off nt
	global_load_dword v118, v[72:73], off nt
	global_load_dword v120, v[74:75], off nt
	global_load_dword v122, v[76:77], off nt
	global_load_dword v124, v[78:79], off nt
	global_load_dword v126, v[80:81], off nt
	global_load_dword v128, v[82:83], off nt
	global_load_dword v130, v[84:85], off nt
	global_load_dword v132, v[18:19], off nt
	ds_read_b128 v[18:21], v17
	ds_read_b128 v[22:25], v17 offset:16
	ds_read_b128 v[64:67], v17 offset:32
	ds_read_b128 v[68:71], v17 offset:48
	ds_read_b128 v[72:75], v17 offset:256
	ds_read_b128 v[76:79], v17 offset:272
	ds_read_b128 v[80:83], v17 offset:512
	ds_read_b128 v[84:87], v17 offset:528
	ds_read_b128 v[88:91], v17 offset:288
	ds_read_b128 v[92:95], v17 offset:304
	ds_read_b128 v[96:99], v17 offset:544
	ds_read_b128 v[100:103], v17 offset:560
	s_waitcnt lgkmcnt(11)
	v_mov_b32_e32 v134, v18
	s_waitcnt lgkmcnt(7)
	v_mov_b32_e32 v135, v72
	v_mov_b32_e32 v72, v19
	v_mov_b32_e32 v18, v20
	v_mov_b32_e32 v19, v74
	s_waitcnt vmcnt(15)
	v_pk_fma_f32 v[14:15], v[2:3], v[134:135], v[14:15] op_sel_hi:[0,1,1]
	s_waitcnt lgkmcnt(5)
	v_fmac_f32_e32 v16, v2, v80
	v_mov_b32_e32 v74, v21
	v_mov_b32_e32 v20, v22
	v_mov_b32_e32 v21, v76
	v_mov_b32_e32 v76, v23
	v_mov_b32_e32 v22, v24
	v_mov_b32_e32 v23, v78
	v_mov_b32_e32 v78, v25
	v_mov_b32_e32 v24, v64
	s_waitcnt lgkmcnt(3)
	v_mov_b32_e32 v25, v88
	v_mov_b32_e32 v88, v65
	v_mov_b32_e32 v64, v66
	v_mov_b32_e32 v65, v90
	v_mov_b32_e32 v90, v67
	v_mov_b32_e32 v66, v68
	s_waitcnt lgkmcnt(2)
	v_mov_b32_e32 v67, v92
	v_mov_b32_e32 v92, v69
	v_mov_b32_e32 v68, v70
	v_mov_b32_e32 v69, v94
	v_mov_b32_e32 v94, v71
	s_waitcnt vmcnt(14)
	v_pk_fma_f32 v[14:15], v[104:105], v[72:73], v[14:15] op_sel_hi:[0,1,1]
	v_fmac_f32_e32 v16, v104, v81
	s_waitcnt vmcnt(13)
	v_pk_fma_f32 v[14:15], v[106:107], v[18:19], v[14:15] op_sel_hi:[0,1,1]
	v_fmac_f32_e32 v16, v106, v82
	s_waitcnt vmcnt(12)
	v_pk_fma_f32 v[14:15], v[108:109], v[74:75], v[14:15] op_sel_hi:[0,1,1]
	v_fmac_f32_e32 v16, v108, v83
	s_waitcnt vmcnt(11)
	v_pk_fma_f32 v[14:15], v[110:111], v[20:21], v[14:15] op_sel_hi:[0,1,1]
	v_fmac_f32_e32 v16, v110, v84
	s_waitcnt vmcnt(10)
	v_pk_fma_f32 v[14:15], v[112:113], v[76:77], v[14:15] op_sel_hi:[0,1,1]
	v_fmac_f32_e32 v16, v112, v85
	s_waitcnt vmcnt(9)
	v_pk_fma_f32 v[14:15], v[114:115], v[22:23], v[14:15] op_sel_hi:[0,1,1]
	v_fmac_f32_e32 v16, v114, v86
	s_waitcnt vmcnt(8)
	v_pk_fma_f32 v[14:15], v[116:117], v[78:79], v[14:15] op_sel_hi:[0,1,1]
	v_fmac_f32_e32 v16, v116, v87
	s_waitcnt vmcnt(7)
	v_pk_fma_f32 v[14:15], v[118:119], v[24:25], v[14:15] op_sel_hi:[0,1,1]
	s_waitcnt lgkmcnt(1)
	v_fmac_f32_e32 v16, v118, v96
	s_waitcnt vmcnt(6)
	v_pk_fma_f32 v[14:15], v[120:121], v[88:89], v[14:15] op_sel_hi:[0,1,1]
	v_fmac_f32_e32 v16, v120, v97
	s_waitcnt vmcnt(5)
	v_pk_fma_f32 v[14:15], v[122:123], v[64:65], v[14:15] op_sel_hi:[0,1,1]
	v_fmac_f32_e32 v16, v122, v98
	s_waitcnt vmcnt(4)
	v_pk_fma_f32 v[14:15], v[124:125], v[90:91], v[14:15] op_sel_hi:[0,1,1]
	v_fmac_f32_e32 v16, v124, v99
	s_waitcnt vmcnt(3)
	v_pk_fma_f32 v[14:15], v[126:127], v[66:67], v[14:15] op_sel_hi:[0,1,1]
	s_waitcnt lgkmcnt(0)
	v_fmac_f32_e32 v16, v126, v100
	s_waitcnt vmcnt(2)
	v_pk_fma_f32 v[14:15], v[128:129], v[92:93], v[14:15] op_sel_hi:[0,1,1]
	v_fmac_f32_e32 v16, v128, v101
	s_waitcnt vmcnt(1)
	v_pk_fma_f32 v[14:15], v[130:131], v[68:69], v[14:15] op_sel_hi:[0,1,1]
	v_fmac_f32_e32 v16, v130, v102
	s_waitcnt vmcnt(0)
	v_pk_fma_f32 v[14:15], v[132:133], v[94:95], v[14:15] op_sel_hi:[0,1,1]
	v_fmac_f32_e32 v16, v132, v103
	s_cbranch_scc0 .LBB0_71
	s_lshl_b32 s1, s22, 1
	s_add_i32 s0, s1, s0
	s_mul_i32 s1, s0, 3
	s_mul_i32 s0, s0, 0x9000
	s_mul_hi_i32 s1, s1, 0x3000
	s_add_u32 s0, s10, s0
	s_addc_u32 s1, s11, s1
	v_lshl_add_u64 v[10:11], v[10:11], 2, s[0:1]
	v_add_co_u32_e32 v12, vcc, 0x3000, v10
	global_store_dword v[10:11], v14, off
	s_nop 0
	v_addc_co_u32_e32 v13, vcc, 0, v11, vcc
	v_add_co_u32_e32 v10, vcc, 0x6000, v10
	global_store_dword v[12:13], v15, off
	s_nop 0
	v_addc_co_u32_e32 v11, vcc, 0, v11, vcc
	global_store_dword v[10:11], v16, off
	s_branch .LBB0_21

.LBB0_188:
	s_andn2_b64 vcc, exec, s[0:1]
	s_cbranch_vccnz .LBB0_192
	v_add_u32_e32 v0, s21, v7
	v_add_u32_e32 v14, 0xfffb1800, v0
	v_lshrrev_b32_e32 v15, 8, v14
	v_bitop3_b32 v0, v15, s51, v7 bitop3:0x48
	v_cmp_eq_u32_e32 vcc, 0, v0
	v_mov_b32_e32 v0, 0
	s_and_saveexec_b64 s[0:1], vcc
	s_cbranch_execz .LBB0_191
	v_ashrrev_i32_e32 v64, 16, v14
	v_ashrrev_i32_e32 v65, 31, v64
	v_lshlrev_b64 v[64:65], 8, v[64:65]
	v_and_or_b32 v0, v15, s51, v64
	v_or_b32_e32 v64, v0, v10
	v_readlane_b32 s64, v253, 2
	v_lshlrev_b64 v[64:65], 8, v[64:65]
	v_readlane_b32 s68, v253, 6
	v_readlane_b32 s69, v253, 7
	v_lshrrev_b32_e32 v0, 6, v14
	v_and_b32_e32 v0, 0xfc, v0
	v_lshl_add_u64 v[64:65], s[68:69], 0, v[64:65]
	v_lshl_add_u64 v[64:65], v[64:65], 0, v[0:1]
	global_load_dword v0, v[64:65], off nt
	v_readlane_b32 s65, v253, 3
	v_readlane_b32 s66, v253, 4
	v_readlane_b32 s67, v253, 5
	v_readlane_b32 s70, v253, 8
	v_readlane_b32 s71, v253, 9
	v_readlane_b32 s72, v253, 10
	v_readlane_b32 s73, v253, 11
	v_readlane_b32 s74, v253, 12
	v_readlane_b32 s75, v253, 13
	v_readlane_b32 s76, v253, 14
	v_readlane_b32 s77, v253, 15
	v_readlane_b32 s78, v253, 16
	v_readlane_b32 s79, v253, 17
	s_waitcnt vmcnt(0)
	v_cvt_pk_bf16_f32 v0, v0, s0

.LBB0_198:
	s_or_saveexec_b64 s[0:1], s[0:1]
	v_ashrrev_i32_e32 v15, 31, v14
	s_and_b32 s24, s45, 0x3c0
	v_lshl_add_u64 v[14:15], v[14:15], 2, s[22:23]
	v_mov_b32_e32 v0, 0
	v_mov_b32_e32 v64, 0
	v_mov_b32_e32 v65, 0
	v_mov_b32_e32 v66, 0
	s_xor_b64 exec, exec, s[0:1]
	s_cbranch_execz .LBB0_200
	v_or_b32_e32 v0, s24, v24
	v_lshlrev_b32_e32 v0, 12, v0
	v_lshl_add_u64 v[64:65], v[14:15], 0, v[0:1]
	v_or_b32_e32 v0, s24, v27
	v_lshlrev_b32_e32 v0, 12, v0
	v_lshl_add_u64 v[66:67], v[14:15], 0, v[0:1]
	v_or_b32_e32 v0, s24, v28
	v_lshlrev_b32_e32 v0, 12, v0
	v_lshl_add_u64 v[68:69], v[14:15], 0, v[0:1]
	v_or_b32_e32 v0, s24, v29
	v_lshlrev_b32_e32 v0, 12, v0
	v_lshl_add_u64 v[70:71], v[14:15], 0, v[0:1]
	v_or_b32_e32 v0, s24, v30
	v_lshlrev_b32_e32 v0, 12, v0
	v_lshl_add_u64 v[72:73], v[14:15], 0, v[0:1]
	v_or_b32_e32 v0, s24, v32
	v_lshlrev_b32_e32 v0, 12, v0
	v_lshl_add_u64 v[74:75], v[14:15], 0, v[0:1]
	v_or_b32_e32 v0, s24, v33
	v_lshlrev_b32_e32 v0, 12, v0
	v_lshl_add_u64 v[76:77], v[14:15], 0, v[0:1]
	v_or_b32_e32 v0, s24, v34
	v_lshlrev_b32_e32 v0, 12, v0
	v_lshl_add_u64 v[78:79], v[14:15], 0, v[0:1]
	global_load_dword v80, v[64:65], off nt
	s_nop 0
	global_load_dword v67, v[66:67], off nt
	s_nop 0
	global_load_dword v68, v[68:69], off nt
	s_nop 0
	global_load_dword v69, v[70:71], off nt
	global_load_dword v0, v[72:73], off nt
	global_load_dword v64, v[74:75], off nt
	global_load_dword v65, v[76:77], off nt
	global_load_dword v66, v[78:79], off nt
	v_add_u32_e32 v70, v25, v26
	s_waitcnt vmcnt(7)
	ds_write_b32 v70, v80
	s_waitcnt vmcnt(6)
	ds_write_b32 v70, v67 offset:1040
	s_waitcnt vmcnt(5)
	ds_write_b32 v70, v68 offset:2080
	s_waitcnt vmcnt(4)
	ds_write_b32 v70, v69 offset:3120

.LBB0_202:
	s_or_saveexec_b64 s[0:1], s[0:1]
	v_mov_b32_e32 v0, 0
	v_mov_b32_e32 v64, 0
	v_mov_b32_e32 v65, 0
	v_mov_b32_e32 v66, 0
	s_xor_b64 exec, exec, s[0:1]
	s_cbranch_execz .LBB0_204
	v_or_b32_e32 v0, s24, v35
	v_lshlrev_b32_e32 v0, 12, v0
	v_lshl_add_u64 v[64:65], v[14:15], 0, v[0:1]
	v_or_b32_e32 v0, s24, v37
	v_lshlrev_b32_e32 v0, 12, v0
	v_lshl_add_u64 v[66:67], v[14:15], 0, v[0:1]
	v_or_b32_e32 v0, s24, v38
	v_lshlrev_b32_e32 v0, 12, v0
	v_lshl_add_u64 v[68:69], v[14:15], 0, v[0:1]
	v_or_b32_e32 v0, s24, v39
	v_lshlrev_b32_e32 v0, 12, v0
	v_lshl_add_u64 v[70:71], v[14:15], 0, v[0:1]
	v_or_b32_e32 v0, s24, v40
	v_lshlrev_b32_e32 v0, 12, v0
	v_lshl_add_u64 v[72:73], v[14:15], 0, v[0:1]
	v_or_b32_e32 v0, s24, v41
	v_lshlrev_b32_e32 v0, 12, v0
	v_lshl_add_u64 v[74:75], v[14:15], 0, v[0:1]
	v_or_b32_e32 v0, s24, v42
	v_lshlrev_b32_e32 v0, 12, v0
	v_lshl_add_u64 v[76:77], v[14:15], 0, v[0:1]
	v_or_b32_e32 v0, s24, v43
	v_lshlrev_b32_e32 v0, 12, v0
	v_lshl_add_u64 v[14:15], v[14:15], 0, v[0:1]
	global_load_dword v78, v[64:65], off nt
	s_nop 0
	global_load_dword v67, v[66:67], off nt
	s_nop 0
	global_load_dword v68, v[68:69], off nt
	s_nop 0
	global_load_dword v69, v[70:71], off nt
	global_load_dword v0, v[72:73], off nt
	global_load_dword v64, v[74:75], off nt
	global_load_dword v65, v[76:77], off nt
	global_load_dword v66, v[14:15], off nt
	v_add_u32_e32 v14, v25, v36
	s_waitcnt vmcnt(7)
	ds_write_b32 v14, v78
	s_waitcnt vmcnt(6)
	ds_write_b32 v14, v67 offset:1040
	s_waitcnt vmcnt(5)
	ds_write_b32 v14, v68 offset:2080
	s_waitcnt vmcnt(4)
	ds_write_b32 v14, v69 offset:3120

.LBB0_213:
	s_or_saveexec_b64 s[22:23], s[22:23]
	s_add_i32 s8, s45, 0x400
	v_ashrrev_i32_e32 v15, 31, v14
	s_and_b32 s8, s8, 0x1c0
	v_lshl_add_u64 v[14:15], v[14:15], 2, s[24:25]
	v_mov_b32_e32 v0, 0
	v_mov_b32_e32 v64, 0
	v_mov_b32_e32 v65, 0
	v_mov_b32_e32 v66, 0
	s_xor_b64 exec, exec, s[22:23]
	s_cbranch_execz .LBB0_215
	v_or_b32_e32 v0, s8, v24
	v_lshlrev_b32_e32 v0, 12, v0
	v_lshl_add_u64 v[64:65], v[14:15], 0, v[0:1]
	v_or_b32_e32 v0, s8, v27
	v_lshlrev_b32_e32 v0, 12, v0
	v_lshl_add_u64 v[66:67], v[14:15], 0, v[0:1]
	v_or_b32_e32 v0, s8, v28
	v_lshlrev_b32_e32 v0, 12, v0
	v_lshl_add_u64 v[68:69], v[14:15], 0, v[0:1]
	v_or_b32_e32 v0, s8, v29
	v_lshlrev_b32_e32 v0, 12, v0
	v_lshl_add_u64 v[70:71], v[14:15], 0, v[0:1]
	v_or_b32_e32 v0, s8, v30
	v_lshlrev_b32_e32 v0, 12, v0
	v_lshl_add_u64 v[72:73], v[14:15], 0, v[0:1]
	v_or_b32_e32 v0, s8, v32
	v_lshlrev_b32_e32 v0, 12, v0
	v_lshl_add_u64 v[74:75], v[14:15], 0, v[0:1]
	v_or_b32_e32 v0, s8, v33
	v_lshlrev_b32_e32 v0, 12, v0
	v_lshl_add_u64 v[76:77], v[14:15], 0, v[0:1]
	v_or_b32_e32 v0, s8, v34
	v_lshlrev_b32_e32 v0, 12, v0
	v_lshl_add_u64 v[78:79], v[14:15], 0, v[0:1]
	global_load_dword v80, v[64:65], off nt
	s_nop 0
	global_load_dword v67, v[66:67], off nt
	s_nop 0
	global_load_dword v68, v[68:69], off nt
	s_nop 0
	global_load_dword v69, v[70:71], off nt
	global_load_dword v0, v[72:73], off nt
	global_load_dword v64, v[74:75], off nt
	global_load_dword v65, v[76:77], off nt
	global_load_dword v66, v[78:79], off nt
	v_add_u32_e32 v70, v25, v26
	s_waitcnt vmcnt(7)
	ds_write_b32 v70, v80
	s_waitcnt vmcnt(6)
	ds_write_b32 v70, v67 offset:1040
	s_waitcnt vmcnt(5)
	ds_write_b32 v70, v68 offset:2080
	s_waitcnt vmcnt(4)
	ds_write_b32 v70, v69 offset:3120

.LBB0_217:
	s_or_saveexec_b64 s[22:23], s[22:23]
	v_mov_b32_e32 v0, 0
	v_mov_b32_e32 v64, 0
	v_mov_b32_e32 v65, 0
	v_mov_b32_e32 v66, 0
	s_xor_b64 exec, exec, s[22:23]
	s_cbranch_execz .LBB0_219
	v_or_b32_e32 v0, s8, v35
	v_lshlrev_b32_e32 v0, 12, v0
	v_lshl_add_u64 v[64:65], v[14:15], 0, v[0:1]
	v_or_b32_e32 v0, s8, v37
	v_lshlrev_b32_e32 v0, 12, v0
	v_lshl_add_u64 v[66:67], v[14:15], 0, v[0:1]
	v_or_b32_e32 v0, s8, v38
	v_lshlrev_b32_e32 v0, 12, v0
	v_lshl_add_u64 v[68:69], v[14:15], 0, v[0:1]
	v_or_b32_e32 v0, s8, v39
	v_lshlrev_b32_e32 v0, 12, v0
	v_lshl_add_u64 v[70:71], v[14:15], 0, v[0:1]
	v_or_b32_e32 v0, s8, v40
	v_lshlrev_b32_e32 v0, 12, v0
	v_lshl_add_u64 v[72:73], v[14:15], 0, v[0:1]
	v_or_b32_e32 v0, s8, v41
	v_lshlrev_b32_e32 v0, 12, v0
	v_lshl_add_u64 v[74:75], v[14:15], 0, v[0:1]
	v_or_b32_e32 v0, s8, v42
	v_lshlrev_b32_e32 v0, 12, v0
	v_lshl_add_u64 v[76:77], v[14:15], 0, v[0:1]
	v_or_b32_e32 v0, s8, v43
	v_lshlrev_b32_e32 v0, 12, v0
	v_lshl_add_u64 v[14:15], v[14:15], 0, v[0:1]
	global_load_dword v78, v[64:65], off nt
	s_nop 0
	global_load_dword v67, v[66:67], off nt
	s_nop 0
	global_load_dword v68, v[68:69], off nt
	s_nop 0
	global_load_dword v69, v[70:71], off nt
	global_load_dword v0, v[72:73], off nt
	global_load_dword v64, v[74:75], off nt
	global_load_dword v65, v[76:77], off nt
	global_load_dword v66, v[14:15], off nt
	v_add_u32_e32 v14, v25, v36
	s_waitcnt vmcnt(7)
	ds_write_b32 v14, v78
	s_waitcnt vmcnt(6)
	ds_write_b32 v14, v67 offset:1040
	s_waitcnt vmcnt(5)
	ds_write_b32 v14, v68 offset:2080
	s_waitcnt vmcnt(4)
	ds_write_b32 v14, v69 offset:3120

.LBB0_228:
	s_or_saveexec_b64 s[0:1], s[0:1]
	s_add_i32 s24, s45, 0x600
	v_ashrrev_i32_e32 v15, 31, v14
	s_and_b32 s24, s24, 0xc0
	v_lshl_add_u64 v[14:15], v[14:15], 2, s[22:23]
	v_mov_b32_e32 v0, 0
	v_mov_b32_e32 v64, 0
	v_mov_b32_e32 v65, 0
	v_mov_b32_e32 v66, 0
	s_xor_b64 exec, exec, s[0:1]
	s_cbranch_execz .LBB0_230
	v_or_b32_e32 v0, s24, v24
	v_lshlrev_b32_e32 v0, 12, v0
	v_lshl_add_u64 v[64:65], v[14:15], 0, v[0:1]
	v_or_b32_e32 v0, s24, v27
	v_lshlrev_b32_e32 v0, 12, v0
	v_lshl_add_u64 v[66:67], v[14:15], 0, v[0:1]
	v_or_b32_e32 v0, s24, v28
	v_lshlrev_b32_e32 v0, 12, v0
	v_lshl_add_u64 v[68:69], v[14:15], 0, v[0:1]
	v_or_b32_e32 v0, s24, v29
	v_lshlrev_b32_e32 v0, 12, v0
	v_lshl_add_u64 v[70:71], v[14:15], 0, v[0:1]
	v_or_b32_e32 v0, s24, v30
	v_lshlrev_b32_e32 v0, 12, v0
	v_lshl_add_u64 v[72:73], v[14:15], 0, v[0:1]
	v_or_b32_e32 v0, s24, v32
	v_lshlrev_b32_e32 v0, 12, v0
	v_lshl_add_u64 v[74:75], v[14:15], 0, v[0:1]
	v_or_b32_e32 v0, s24, v33
	v_lshlrev_b32_e32 v0, 12, v0
	v_lshl_add_u64 v[76:77], v[14:15], 0, v[0:1]
	v_or_b32_e32 v0, s24, v34
	v_lshlrev_b32_e32 v0, 12, v0
	v_lshl_add_u64 v[78:79], v[14:15], 0, v[0:1]
	global_load_dword v80, v[64:65], off nt
	s_nop 0
	global_load_dword v67, v[66:67], off nt
	s_nop 0
	global_load_dword v68, v[68:69], off nt
	s_nop 0
	global_load_dword v69, v[70:71], off nt
	global_load_dword v0, v[72:73], off nt
	global_load_dword v64, v[74:75], off nt
	global_load_dword v65, v[76:77], off nt
	global_load_dword v66, v[78:79], off nt
	v_add_u32_e32 v70, v25, v26
	s_waitcnt vmcnt(7)
	ds_write_b32 v70, v80
	s_waitcnt vmcnt(6)
	ds_write_b32 v70, v67 offset:1040
	s_waitcnt vmcnt(5)
	ds_write_b32 v70, v68 offset:2080
	s_waitcnt vmcnt(4)
	ds_write_b32 v70, v69 offset:3120

.LBB0_243:
	s_or_saveexec_b64 s[0:1], s[0:1]
	s_add_i32 s24, s45, 0x800
	v_ashrrev_i32_e32 v15, 31, v14
	s_and_b32 s24, s24, 0xc0
	v_lshl_add_u64 v[14:15], v[14:15], 2, s[22:23]
	v_mov_b32_e32 v0, 0
	v_mov_b32_e32 v64, 0
	v_mov_b32_e32 v65, 0
	v_mov_b32_e32 v66, 0
	s_xor_b64 exec, exec, s[0:1]
	s_cbranch_execz .LBB0_245
	v_or_b32_e32 v0, s24, v24
	v_lshlrev_b32_e32 v0, 12, v0
	v_lshl_add_u64 v[64:65], v[14:15], 0, v[0:1]
	v_or_b32_e32 v0, s24, v27
	v_lshlrev_b32_e32 v0, 12, v0
	v_lshl_add_u64 v[66:67], v[14:15], 0, v[0:1]
	v_or_b32_e32 v0, s24, v28
	v_lshlrev_b32_e32 v0, 12, v0
	v_lshl_add_u64 v[68:69], v[14:15], 0, v[0:1]
	v_or_b32_e32 v0, s24, v29
	v_lshlrev_b32_e32 v0, 12, v0
	v_lshl_add_u64 v[70:71], v[14:15], 0, v[0:1]
	v_or_b32_e32 v0, s24, v30
	v_lshlrev_b32_e32 v0, 12, v0
	v_lshl_add_u64 v[72:73], v[14:15], 0, v[0:1]
	v_or_b32_e32 v0, s24, v32
	v_lshlrev_b32_e32 v0, 12, v0
	v_lshl_add_u64 v[74:75], v[14:15], 0, v[0:1]
	v_or_b32_e32 v0, s24, v33
	v_lshlrev_b32_e32 v0, 12, v0
	v_lshl_add_u64 v[76:77], v[14:15], 0, v[0:1]
	v_or_b32_e32 v0, s24, v34
	v_lshlrev_b32_e32 v0, 12, v0
	v_lshl_add_u64 v[78:79], v[14:15], 0, v[0:1]
	global_load_dword v80, v[64:65], off nt
	s_nop 0
	global_load_dword v67, v[66:67], off nt
	s_nop 0
	global_load_dword v68, v[68:69], off nt
	s_nop 0
	global_load_dword v69, v[70:71], off nt
	global_load_dword v0, v[72:73], off nt
	global_load_dword v64, v[74:75], off nt
	global_load_dword v65, v[76:77], off nt
	global_load_dword v66, v[78:79], off nt
	v_add_u32_e32 v70, v25, v26
	s_waitcnt vmcnt(7)
	ds_write_b32 v70, v80
	s_waitcnt vmcnt(6)
	ds_write_b32 v70, v67 offset:1040
	s_waitcnt vmcnt(5)
	ds_write_b32 v70, v68 offset:2080
	s_waitcnt vmcnt(4)
	ds_write_b32 v70, v69 offset:3120

.LBB0_258:
	s_or_saveexec_b64 s[0:1], s[0:1]
	s_add_i32 s24, s45, 0x900
	v_ashrrev_i32_e32 v15, 31, v14
	s_and_b32 s24, s24, 64
	v_lshl_add_u64 v[14:15], v[14:15], 2, s[22:23]
	v_mov_b32_e32 v0, 0
	v_mov_b32_e32 v64, 0
	v_mov_b32_e32 v65, 0
	v_mov_b32_e32 v66, 0
	s_xor_b64 exec, exec, s[0:1]
	s_cbranch_execz .LBB0_260
	v_or_b32_e32 v0, s24, v24
	v_lshlrev_b32_e32 v0, 12, v0
	v_lshl_add_u64 v[64:65], v[14:15], 0, v[0:1]
	v_or_b32_e32 v0, s24, v27
	v_lshlrev_b32_e32 v0, 12, v0
	v_lshl_add_u64 v[66:67], v[14:15], 0, v[0:1]
	v_or_b32_e32 v0, s24, v28
	v_lshlrev_b32_e32 v0, 12, v0
	v_lshl_add_u64 v[68:69], v[14:15], 0, v[0:1]
	v_or_b32_e32 v0, s24, v29
	v_lshlrev_b32_e32 v0, 12, v0
	v_lshl_add_u64 v[70:71], v[14:15], 0, v[0:1]
	v_or_b32_e32 v0, s24, v30
	v_lshlrev_b32_e32 v0, 12, v0
	v_lshl_add_u64 v[72:73], v[14:15], 0, v[0:1]
	v_or_b32_e32 v0, s24, v32
	v_lshlrev_b32_e32 v0, 12, v0
	v_lshl_add_u64 v[74:75], v[14:15], 0, v[0:1]
	v_or_b32_e32 v0, s24, v33
	v_lshlrev_b32_e32 v0, 12, v0
	v_lshl_add_u64 v[76:77], v[14:15], 0, v[0:1]
	v_or_b32_e32 v0, s24, v34
	v_lshlrev_b32_e32 v0, 12, v0
	v_lshl_add_u64 v[78:79], v[14:15], 0, v[0:1]
	global_load_dword v80, v[64:65], off nt
	s_nop 0
	global_load_dword v67, v[66:67], off nt
	s_nop 0
	global_load_dword v68, v[68:69], off nt
	s_nop 0
	global_load_dword v69, v[70:71], off nt
	global_load_dword v0, v[72:73], off nt
	global_load_dword v64, v[74:75], off nt
	global_load_dword v65, v[76:77], off nt
	global_load_dword v66, v[78:79], off nt
	v_add_u32_e32 v70, v25, v26
	s_waitcnt vmcnt(7)
	ds_write_b32 v70, v80
	s_waitcnt vmcnt(6)
	ds_write_b32 v70, v67 offset:1040
	s_waitcnt vmcnt(5)
	ds_write_b32 v70, v68 offset:2080
	s_waitcnt vmcnt(4)
	ds_write_b32 v70, v69 offset:3120

.LBB0_273:
	s_or_saveexec_b64 s[22:23], s[22:23]
	v_ashrrev_i32_e32 v15, 31, v14
	s_lshl_b32 s8, s8, 6
	v_lshl_add_u64 v[14:15], v[14:15], 2, s[24:25]
	v_mov_b32_e32 v0, 0
	v_mov_b32_e32 v64, 0
	v_mov_b32_e32 v65, 0
	v_mov_b32_e32 v66, 0
	s_xor_b64 exec, exec, s[22:23]
	s_cbranch_execz .LBB0_275
	v_or_b32_e32 v0, s8, v24
	v_mul_lo_u32 v0, v0, s53
	v_lshl_add_u64 v[64:65], v[0:1], 2, v[14:15]
	v_or_b32_e32 v0, s8, v27
	v_mul_lo_u32 v0, v0, s53
	v_lshl_add_u64 v[66:67], v[0:1], 2, v[14:15]
	v_or_b32_e32 v0, s8, v28
	v_mul_lo_u32 v0, v0, s53
	v_lshl_add_u64 v[68:69], v[0:1], 2, v[14:15]
	v_or_b32_e32 v0, s8, v29
	v_mul_lo_u32 v0, v0, s53
	v_lshl_add_u64 v[70:71], v[0:1], 2, v[14:15]
	v_or_b32_e32 v0, s8, v30
	v_mul_lo_u32 v0, v0, s53
	v_lshl_add_u64 v[72:73], v[0:1], 2, v[14:15]
	v_or_b32_e32 v0, s8, v32
	v_mul_lo_u32 v0, v0, s53
	v_lshl_add_u64 v[74:75], v[0:1], 2, v[14:15]
	v_or_b32_e32 v0, s8, v33
	v_mul_lo_u32 v0, v0, s53
	v_lshl_add_u64 v[76:77], v[0:1], 2, v[14:15]
	v_or_b32_e32 v0, s8, v34
	v_mul_lo_u32 v0, v0, s53
	v_lshl_add_u64 v[78:79], v[0:1], 2, v[14:15]
	global_load_dword v80, v[64:65], off nt
	s_nop 0
	global_load_dword v67, v[66:67], off nt
	s_nop 0
	global_load_dword v68, v[68:69], off nt
	s_nop 0
	global_load_dword v69, v[70:71], off nt
	global_load_dword v0, v[72:73], off nt
	global_load_dword v64, v[74:75], off nt
	global_load_dword v65, v[76:77], off nt
	global_load_dword v66, v[78:79], off nt
	v_add_u32_e32 v70, v25, v26
	s_waitcnt vmcnt(7)
	ds_write_b32 v70, v80
	s_waitcnt vmcnt(6)
	ds_write_b32 v70, v67 offset:1040
	s_waitcnt vmcnt(5)
	ds_write_b32 v70, v68 offset:2080
	s_waitcnt vmcnt(4)
	ds_write_b32 v70, v69 offset:3120

.LBB0_277:
	s_or_saveexec_b64 s[22:23], s[22:23]
	v_mov_b32_e32 v0, 0
	v_mov_b32_e32 v65, 0
	v_mov_b32_e32 v66, 0
	v_mov_b32_e32 v67, 0
	s_xor_b64 exec, exec, s[22:23]
	s_cbranch_execz .LBB0_279
	v_or_b32_e32 v0, s8, v35
	v_mul_lo_u32 v0, v0, s53
	v_lshl_add_u64 v[66:67], v[0:1], 2, v[14:15]
	v_or_b32_e32 v0, s8, v37
	v_mul_lo_u32 v0, v0, s53
	v_lshl_add_u64 v[68:69], v[0:1], 2, v[14:15]
	v_or_b32_e32 v0, s8, v38
	v_mul_lo_u32 v0, v0, s53
	v_lshl_add_u64 v[70:71], v[0:1], 2, v[14:15]
	v_or_b32_e32 v0, s8, v39
	v_mul_lo_u32 v0, v0, s53
	v_lshl_add_u64 v[72:73], v[0:1], 2, v[14:15]
	v_or_b32_e32 v0, s8, v40
	v_mul_lo_u32 v0, v0, s53
	v_lshl_add_u64 v[74:75], v[0:1], 2, v[14:15]
	v_or_b32_e32 v0, s8, v41
	v_mul_lo_u32 v0, v0, s53
	v_lshl_add_u64 v[76:77], v[0:1], 2, v[14:15]
	v_or_b32_e32 v0, s8, v42
	v_mul_lo_u32 v0, v0, s53
	v_lshl_add_u64 v[78:79], v[0:1], 2, v[14:15]
	v_or_b32_e32 v0, s8, v43
	v_mul_lo_u32 v0, v0, s53
	v_lshl_add_u64 v[14:15], v[0:1], 2, v[14:15]
	global_load_dword v80, v[66:67], off nt
	s_nop 0
	global_load_dword v68, v[68:69], off nt
	s_nop 0
	global_load_dword v69, v[70:71], off nt
	s_nop 0
	global_load_dword v70, v[72:73], off nt
	global_load_dword v0, v[74:75], off nt
	global_load_dword v65, v[76:77], off nt
	global_load_dword v66, v[78:79], off nt
	global_load_dword v67, v[14:15], off nt
	s_waitcnt vmcnt(7)
	ds_write_b32 v64, v80
	s_waitcnt vmcnt(6)
	ds_write_b32 v64, v68 offset:1040
	s_waitcnt vmcnt(5)
	ds_write_b32 v64, v69 offset:2080
	s_waitcnt vmcnt(4)
	ds_write_b32 v64, v70 offset:3120

.LBB0_283:
	s_andn2_b64 vcc, exec, s[0:1]
	s_cbranch_vccnz .LBB0_130
	v_add_u32_e32 v14, s21, v7
	s_mov_b32 s0, 0x38e38e39
	v_mul_hi_i32 v0, v14, s0
	v_lshrrev_b32_e32 v15, 31, v0
	v_ashrrev_i32_e32 v0, 11, v0
	v_add_u32_e32 v0, v0, v15
	v_mul_i32_i24_e32 v64, 0x2400, v0
	v_sub_u32_e32 v66, v14, v64
	v_mul_i32_i24_e32 v15, 0x2aab, v66
	v_lshrrev_b32_e32 v63, 31, v15
	v_lshrrev_b32_e32 v15, 25, v15
	v_add_u16_e32 v15, v15, v63
	v_mul_lo_u16_e32 v15, 0xc00, v15
	v_sub_u16_e32 v15, v66, v15
	v_ashrrev_i32_e32 v65, 31, v64
	v_bfe_i32 v15, v15, 0, 16
	s_movk_i32 s0, 0xc00
	v_ashrrev_i32_e32 v67, 31, v66
	v_lshl_add_u64 v[64:65], v[64:65], 2, s[10:11]
	v_mad_i32_i24 v68, v0, s0, v15
	v_readlane_b32 s64, v253, 2
	v_lshl_add_u64 v[64:65], v[66:67], 2, v[64:65]
	s_mov_b32 s0, 0x12000
	v_ashrrev_i32_e32 v69, 31, v68
	v_readlane_b32 s65, v253, 3
	v_add_co_u32_e32 v66, vcc, s0, v64
	s_nop 0
	v_lshl_add_u64 v[68:69], v[68:69], 2, s[64:65]
	v_addc_co_u32_e32 v67, vcc, 0, v65, vcc
	s_mov_b32 s0, 0x24000
	global_load_dword v0, v[68:69], off nt
	v_add_co_u32_e32 v68, vcc, s0, v64
	s_mov_b32 s0, 0x36000
	s_nop 0
	v_addc_co_u32_e32 v69, vcc, 0, v65, vcc
	v_add_co_u32_e32 v70, vcc, s0, v64
	s_mov_b32 s0, 0x48000
	s_nop 0
	v_addc_co_u32_e32 v71, vcc, 0, v65, vcc
	v_add_co_u32_e32 v72, vcc, s0, v64
	s_mov_b32 s0, 0x5a000
	s_nop 0
	v_addc_co_u32_e32 v73, vcc, 0, v65, vcc
	v_add_co_u32_e32 v74, vcc, s0, v64
	v_readlane_b32 s0, v253, 29
	s_nop 0
	v_addc_co_u32_e32 v75, vcc, 0, v65, vcc
	v_add_co_u32_e32 v76, vcc, s54, v64
	v_readlane_b32 s1, v253, 30
	s_nop 0
	v_addc_co_u32_e32 v77, vcc, 0, v65, vcc
	v_add_co_u32_e32 v78, vcc, s55, v64
	v_readlane_b32 s66, v253, 4
	s_nop 0
	v_addc_co_u32_e32 v79, vcc, 0, v65, vcc
	global_load_dword v15, v[64:65], off nt
	global_load_dword v63, v[66:67], off nt
	global_load_dword v80, v[68:69], off nt
	global_load_dword v81, v[70:71], off nt
	global_load_dword v82, v[72:73], off nt
	global_load_dword v83, v[74:75], off nt
	global_load_dword v84, v[76:77], off nt
	global_load_dword v85, v[78:79], off nt
	v_add_co_u32_e32 v66, vcc, s56, v64
	v_readlane_b32 s67, v253, 5
	s_nop 0
	v_addc_co_u32_e32 v67, vcc, 0, v65, vcc
	v_add_co_u32_e32 v68, vcc, s57, v64
	v_readlane_b32 s68, v253, 6
	s_nop 0
	v_addc_co_u32_e32 v69, vcc, 0, v65, vcc
	v_add_co_u32_e32 v70, vcc, s58, v64
	v_readlane_b32 s69, v253, 7
	s_nop 0
	v_addc_co_u32_e32 v71, vcc, 0, v65, vcc
	v_add_co_u32_e32 v72, vcc, s59, v64
	v_readlane_b32 s70, v253, 8
	s_nop 0
	v_addc_co_u32_e32 v73, vcc, 0, v65, vcc
	v_add_co_u32_e32 v74, vcc, s60, v64
	v_readlane_b32 s71, v253, 9
	s_nop 0
	v_addc_co_u32_e32 v75, vcc, 0, v65, vcc
	v_add_co_u32_e32 v76, vcc, s61, v64
	v_readlane_b32 s72, v253, 10
	s_nop 0
	v_addc_co_u32_e32 v77, vcc, 0, v65, vcc
	v_add_co_u32_e32 v78, vcc, 0xfc000, v64
	v_readlane_b32 s73, v253, 11
	s_nop 0
	v_addc_co_u32_e32 v79, vcc, 0, v65, vcc
	v_add_co_u32_e32 v64, vcc, 0x10e000, v64
	v_readlane_b32 s74, v253, 12
	s_nop 0
	v_addc_co_u32_e32 v65, vcc, 0, v65, vcc
	global_load_dword v66, v[66:67], off nt
	s_nop 0
	global_load_dword v67, v[68:69], off nt
	s_nop 0
	global_load_dword v68, v[70:71], off nt
	global_load_dword v69, v[72:73], off nt
	s_nop 0
	global_load_dword v70, v[74:75], off nt
	global_load_dword v71, v[76:77], off nt
	global_load_dword v72, v[78:79], off nt
	s_nop 0
	global_load_dword v64, v[64:65], off nt
	v_readlane_b32 s75, v253, 13
	v_readlane_b32 s76, v253, 14
	v_readlane_b32 s77, v253, 15
	v_readlane_b32 s78, v253, 16
	v_readlane_b32 s79, v253, 17
	s_waitcnt vmcnt(15)
	v_add_f32_e32 v0, v0, v15
	s_waitcnt vmcnt(14)
	v_add_f32_e32 v0, v0, v63
	s_waitcnt vmcnt(13)
	v_add_f32_e32 v0, v0, v80
	s_waitcnt vmcnt(12)
	v_add_f32_e32 v0, v0, v81
	s_waitcnt vmcnt(11)
	v_add_f32_e32 v0, v0, v82
	s_waitcnt vmcnt(10)
	v_add_f32_e32 v0, v0, v83
	s_waitcnt vmcnt(9)
	v_add_f32_e32 v0, v0, v84
	s_waitcnt vmcnt(8)
	v_add_f32_e32 v0, v0, v85
	v_ashrrev_i32_e32 v15, 31, v14
	v_lshl_add_u64 v[14:15], v[14:15], 2, s[0:1]
	s_waitcnt vmcnt(7)
	v_add_f32_e32 v0, v0, v66
	s_waitcnt vmcnt(6)
	v_add_f32_e32 v0, v0, v67
	s_waitcnt vmcnt(5)
	v_add_f32_e32 v0, v0, v68
	s_waitcnt vmcnt(4)
	v_add_f32_e32 v0, v0, v69
	s_waitcnt vmcnt(3)
	v_add_f32_e32 v0, v0, v70
	s_waitcnt vmcnt(2)
	v_add_f32_e32 v0, v0, v71
	s_waitcnt vmcnt(1)
	v_add_f32_e32 v0, v0, v72
	s_waitcnt vmcnt(0)
	v_add_f32_e32 v0, v0, v64
	global_store_dword v[14:15], v0, off
	s_branch .LBB0_130

.LBB0_1053:
	ds_bpermute_b32 v0, v146, v148
	s_lshl_b32 s68, s17, 7
	v_lshlrev_b32_e32 v10, 3, v132
	v_mov_b32_e32 v11, v4
	s_waitcnt lgkmcnt(0)
	v_add_f32_e32 v0, v148, v0
	v_div_scale_f32 v1, s[0:1], v0, v0, 1.0
	v_rcp_f32_e32 v2, v1
	s_add_i32 s0, s19, s18
	v_fma_f32 v3, -v1, v2, 1.0
	v_fmac_f32_e32 v2, v3, v2
	v_div_scale_f32 v3, vcc, 1.0, v0, 1.0
	v_mul_f32_e32 v5, v3, v2
	v_fma_f32 v6, -v1, v5, v3
	v_fmac_f32_e32 v5, v6, v2
	v_fma_f32 v1, -v1, v5, v3
	v_div_fmas_f32 v1, v1, v2, v5
	v_add_u32_e32 v2, s0, v133
	v_ashrrev_i32_e32 v3, 31, v2
	v_mov_b64_e32 v[6:7], s[26:27]
	v_mad_i64_i32 v[8:9], s[0:1], v2, s92, v[6:7]
	v_lshlrev_b64 v[2:3], 9, v[2:3]
	v_sub_co_u32_e32 v2, vcc, 0, v2
	v_lshl_add_u64 v[6:7], v[8:9], 0, s[68:69]
	s_nop 0
	v_subb_co_u32_e32 v3, vcc, 0, v3, vcc
	v_lshl_add_u64 v[2:3], v[8:9], 0, v[2:3]
	v_lshl_add_u64 v[12:13], v[6:7], 0, v[10:11]
	s_mov_b64 s[0:1], 0x4512600
	v_lshl_add_u64 v[2:3], v[2:3], 0, s[68:69]
	v_lshl_add_u64 v[6:7], v[12:13], 0, s[0:1]
	v_lshl_add_u64 v[8:9], v[2:3], 0, v[10:11]
	s_mov_b64 s[0:1], 0x6d12400
	v_lshl_add_u64 v[2:3], v[8:9], 0, s[0:1]
	v_div_fixup_f32 v0, v1, v0, 1.0
	global_load_dwordx2 v[150:151], v[6:7], off nt
	global_load_dwordx2 v[152:153], v[6:7], off offset:16 nt
	global_load_dwordx2 v[154:155], v[6:7], off offset:32 nt
	global_load_dwordx2 v[156:157], v[6:7], off offset:48 nt
	global_load_dwordx2 v[158:159], v[6:7], off offset:64 nt
	global_load_dwordx2 v[160:161], v[6:7], off offset:80 nt
	global_load_dwordx2 v[162:163], v[6:7], off offset:96 nt
	global_load_dwordx2 v[164:165], v[6:7], off offset:112 nt
	s_waitcnt vmcnt(7)
	v_pk_mul_f32 v[12:13], v[32:33], v[0:1] op_sel_hi:[1,0]
	v_lshlrev_b32_e32 v14, 16, v150
	v_and_b32_e32 v15, 0xffff0000, v150
	v_pk_mul_f32 v[12:13], v[12:13], v[14:15]
	v_pk_mul_f32 v[8:9], v[34:35], v[0:1] op_sel_hi:[1,0]
	v_cvt_pk_bf16_f32 v10, v12, v13
	v_lshlrev_b32_e32 v14, 16, v151
	v_and_b32_e32 v15, 0xffff0000, v151
	v_pk_mul_f32 v[8:9], v[8:9], v[14:15]
	s_nop 0
	v_cvt_pk_bf16_f32 v11, v8, v9
	global_store_dwordx2 v[2:3], v[10:11], off
	s_waitcnt vmcnt(7)
	v_pk_mul_f32 v[12:13], v[36:37], v[0:1] op_sel_hi:[1,0]
	v_lshlrev_b32_e32 v14, 16, v152
	v_and_b32_e32 v15, 0xffff0000, v152
	v_pk_mul_f32 v[12:13], v[12:13], v[14:15]
	v_pk_mul_f32 v[8:9], v[38:39], v[0:1] op_sel_hi:[1,0]
	v_cvt_pk_bf16_f32 v10, v12, v13
	v_lshlrev_b32_e32 v14, 16, v153
	v_and_b32_e32 v15, 0xffff0000, v153
	v_pk_mul_f32 v[8:9], v[8:9], v[14:15]
	s_nop 0
	v_cvt_pk_bf16_f32 v11, v8, v9
	global_store_dwordx2 v[2:3], v[10:11], off offset:16
	s_waitcnt vmcnt(7)
	v_pk_mul_f32 v[12:13], v[40:41], v[0:1] op_sel_hi:[1,0]
	v_lshlrev_b32_e32 v14, 16, v154
	v_and_b32_e32 v15, 0xffff0000, v154
	v_pk_mul_f32 v[12:13], v[12:13], v[14:15]
	v_pk_mul_f32 v[8:9], v[42:43], v[0:1] op_sel_hi:[1,0]
	v_cvt_pk_bf16_f32 v10, v12, v13
	v_lshlrev_b32_e32 v14, 16, v155
	v_and_b32_e32 v15, 0xffff0000, v155
	v_pk_mul_f32 v[8:9], v[8:9], v[14:15]
	s_nop 0
	v_cvt_pk_bf16_f32 v11, v8, v9
	global_store_dwordx2 v[2:3], v[10:11], off offset:32
	s_waitcnt vmcnt(7)
	v_pk_mul_f32 v[12:13], v[44:45], v[0:1] op_sel_hi:[1,0]
	v_lshlrev_b32_e32 v14, 16, v156
	v_and_b32_e32 v15, 0xffff0000, v156
	v_pk_mul_f32 v[12:13], v[12:13], v[14:15]
	v_pk_mul_f32 v[8:9], v[46:47], v[0:1] op_sel_hi:[1,0]
	v_cvt_pk_bf16_f32 v10, v12, v13
	v_lshlrev_b32_e32 v14, 16, v157
	v_and_b32_e32 v15, 0xffff0000, v157
	v_pk_mul_f32 v[8:9], v[8:9], v[14:15]
	s_nop 0
	v_cvt_pk_bf16_f32 v11, v8, v9
	global_store_dwordx2 v[2:3], v[10:11], off offset:48
	s_waitcnt vmcnt(7)
	v_pk_mul_f32 v[12:13], v[16:17], v[0:1] op_sel_hi:[1,0]
	v_lshlrev_b32_e32 v14, 16, v158
	v_and_b32_e32 v15, 0xffff0000, v158
	v_pk_mul_f32 v[12:13], v[12:13], v[14:15]
	v_pk_mul_f32 v[8:9], v[18:19], v[0:1] op_sel_hi:[1,0]
	v_cvt_pk_bf16_f32 v10, v12, v13
	v_lshlrev_b32_e32 v14, 16, v159
	v_and_b32_e32 v15, 0xffff0000, v159
	v_pk_mul_f32 v[8:9], v[8:9], v[14:15]
	s_nop 0
	v_cvt_pk_bf16_f32 v11, v8, v9
	global_store_dwordx2 v[2:3], v[10:11], off offset:64
	s_waitcnt vmcnt(7)
	v_pk_mul_f32 v[12:13], v[20:21], v[0:1] op_sel_hi:[1,0]
	v_lshlrev_b32_e32 v14, 16, v160
	v_and_b32_e32 v15, 0xffff0000, v160
	v_pk_mul_f32 v[12:13], v[12:13], v[14:15]
	v_pk_mul_f32 v[8:9], v[22:23], v[0:1] op_sel_hi:[1,0]
	v_cvt_pk_bf16_f32 v10, v12, v13
	v_lshlrev_b32_e32 v14, 16, v161
	v_and_b32_e32 v15, 0xffff0000, v161
	v_pk_mul_f32 v[8:9], v[8:9], v[14:15]
	s_nop 0
	v_cvt_pk_bf16_f32 v11, v8, v9
	global_store_dwordx2 v[2:3], v[10:11], off offset:80
	s_waitcnt vmcnt(7)
	v_pk_mul_f32 v[12:13], v[24:25], v[0:1] op_sel_hi:[1,0]
	v_lshlrev_b32_e32 v14, 16, v162
	v_and_b32_e32 v15, 0xffff0000, v162
	v_pk_mul_f32 v[12:13], v[12:13], v[14:15]
	v_pk_mul_f32 v[8:9], v[26:27], v[0:1] op_sel_hi:[1,0]
	v_cvt_pk_bf16_f32 v10, v12, v13
	v_lshlrev_b32_e32 v14, 16, v163
	v_and_b32_e32 v15, 0xffff0000, v163
	v_pk_mul_f32 v[8:9], v[8:9], v[14:15]
	s_nop 0
	v_cvt_pk_bf16_f32 v11, v8, v9
	global_store_dwordx2 v[2:3], v[10:11], off offset:96
	s_waitcnt vmcnt(7)
	v_pk_mul_f32 v[12:13], v[28:29], v[0:1] op_sel_hi:[1,0]
	v_lshlrev_b32_e32 v14, 16, v164
	v_and_b32_e32 v15, 0xffff0000, v164
	v_pk_mul_f32 v[12:13], v[12:13], v[14:15]
	v_pk_mul_f32 v[8:9], v[30:31], v[0:1] op_sel_hi:[1,0]
	v_cvt_pk_bf16_f32 v10, v12, v13
	v_lshlrev_b32_e32 v14, 16, v165
	v_and_b32_e32 v15, 0xffff0000, v165
	v_pk_mul_f32 v[8:9], v[8:9], v[14:15]
	s_nop 0
	v_cvt_pk_bf16_f32 v11, v8, v9
	global_store_dwordx2 v[2:3], v[10:11], off offset:112

.LBB0_1160:
	v_ashrrev_i32_e32 v0, 1, v144
	s_movk_i32 s4, 0xffe0
	v_bfe_u32 v132, v144, 5, 1
	v_bfi_b32 v133, s4, v0, v144
	v_mov_b64_e32 v[0:1], s[0:1]
	v_mad_i64_i32 v[0:1], s[0:1], v133, s50, v[0:1]
	v_lshlrev_b32_e32 v16, 4, v132
	v_mov_b32_e32 v17, v4
	v_lshl_add_u64 v[6:7], v[0:1], 0, v[16:17]
	global_load_dwordx4 v[96:99], v[6:7], off nt
	global_load_dwordx4 v[100:103], v[6:7], off offset:32 nt
	global_load_dwordx4 v[104:107], v[6:7], off offset:64 nt
	global_load_dwordx4 v[108:111], v[6:7], off offset:96 nt
	v_ashrrev_i32_e32 v145, 31, v144
	v_lshl_add_u64 v[0:1], v[144:145], 4, s[12:13]
	global_load_dwordx4 v[0:3], v[0:1], off
	s_nop 0
	global_load_dwordx4 v[112:115], v[6:7], off offset:128 nt
	global_load_dwordx4 v[116:119], v[6:7], off offset:160 nt
	v_mov_b32_e32 v6, v4
	v_mov_b32_e32 v7, v4
	v_lshlrev_b64 v[14:15], 3, v[144:145]
	v_mov_b32_e32 v5, v4
	s_movk_i32 s0, 0xff
	v_cmp_lt_i32_e64 s[0:1], s0, v144
	v_cmp_gt_i32_e64 s[4:5], s33, v144
	v_lshl_add_u64 v[8:9], v[14:15], 1, s[14:15]
	s_waitcnt vmcnt(2)
	v_mov_b64_e32 v[86:87], v[6:7]
	v_mov_b64_e32 v[84:85], v[4:5]
	v_mov_b64_e32 v[82:83], v[2:3]
	v_mov_b64_e32 v[80:81], v[0:1]
	s_and_saveexec_b64 s[22:23], s[4:5]
	s_cbranch_execz .LBB0_1162
	global_load_dwordx4 v[10:13], v[8:9], off
	v_mov_b64_e32 v[86:87], v[6:7]
	v_mov_b64_e32 v[84:85], v[4:5]
	v_mov_b64_e32 v[82:83], v[2:3]
	v_mov_b64_e32 v[80:81], v[0:1]
	s_waitcnt vmcnt(0)
	v_mov_b32_e32 v84, v10
	v_mov_b32_e32 v85, v11
	v_mov_b32_e32 v86, v12
	v_mov_b32_e32 v87, v13

.Lwout_l0:
	s_cmp_lt_u32 s11, 32
	s_cselect_b32 s12, s36, s38
	s_cselect_b32 s13, s37, s39
	s_and_b32 s0, s11, 31
	s_lshl_b32 s0, s0, 20
	s_add_u32 s12, s12, s0
	s_addc_u32 s13, s13, 0
	s_lshl_b32 s0, s16, 2
	s_add_u32 s12, s12, s0
	s_addc_u32 s13, s13, 0
	s_add_u32 s0, s12, 0x0
	s_addc_u32 s1, s13, 0
	global_load_dwordx4 v[130:133], v232, s[0:1] nt
	global_load_dwordx4 v[134:137], v232, s[0:1] offset:16 nt
	s_add_u32 s0, s12, 0x10000
	s_addc_u32 s1, s13, 0
	global_load_dwordx4 v[156:159], v232, s[0:1] nt
	global_load_dwordx4 v[160:163], v232, s[0:1] offset:16 nt
	s_add_u32 s0, s12, 0x20000
	s_addc_u32 s1, s13, 0
	global_load_dwordx4 v[164:167], v232, s[0:1] nt
	global_load_dwordx4 v[168:171], v232, s[0:1] offset:16 nt
	s_add_u32 s0, s12, 0x30000
	s_addc_u32 s1, s13, 0
	global_load_dwordx4 v[172:175], v232, s[0:1] nt
	global_load_dwordx4 v[176:179], v232, s[0:1] offset:16 nt
	s_add_u32 s0, s12, 0x80000
	s_addc_u32 s1, s13, 0
	global_load_dwordx4 v[198:201], v232, s[0:1] nt
	global_load_dwordx4 v[202:205], v232, s[0:1] offset:16 nt
	s_add_u32 s0, s12, 0x90000
	s_addc_u32 s1, s13, 0
	global_load_dwordx4 v[206:209], v232, s[0:1] nt
	global_load_dwordx4 v[210:213], v232, s[0:1] offset:16 nt
	s_waitcnt vmcnt(10)
	v_pk_fma_f32 v[126:127], v[126:127], v[182:183], v[130:131]
	v_pk_fma_f32 v[128:129], v[128:129], v[184:185], v[132:133]
	v_pk_fma_f32 v[122:123], v[122:123], v[186:187], v[134:135]
	v_pk_fma_f32 v[124:125], v[124:125], v[188:189], v[136:137]
	v_cvt_pk_bf16_f32 v126, v126, v127
	v_cvt_pk_bf16_f32 v127, v128, v129
	v_cvt_pk_bf16_f32 v128, v122, v123
	v_cvt_pk_bf16_f32 v129, v124, v125
	s_add_u32 s8, s14, 0x0
	s_addc_u32 s9, s15, 0
	global_store_dwordx4 v233, v[126:129], s[8:9]
	s_add_u32 s0, s12, 0xa0000
	s_addc_u32 s1, s13, 0
	global_load_dwordx4 v[130:133], v232, s[0:1] nt
	global_load_dwordx4 v[134:137], v232, s[0:1] offset:16 nt
	s_waitcnt vmcnt(11)
	v_pk_fma_f32 v[118:119], v[118:119], v[182:183], v[156:157]
	v_pk_fma_f32 v[120:121], v[120:121], v[184:185], v[158:159]
	v_pk_fma_f32 v[114:115], v[114:115], v[186:187], v[160:161]
	v_pk_fma_f32 v[116:117], v[116:117], v[188:189], v[162:163]
	v_cvt_pk_bf16_f32 v118, v118, v119
	v_cvt_pk_bf16_f32 v119, v120, v121
	v_cvt_pk_bf16_f32 v120, v114, v115
	v_cvt_pk_bf16_f32 v121, v116, v117
	s_add_u32 s8, s14, 0x8000
	s_addc_u32 s9, s15, 0
	global_store_dwordx4 v233, v[118:121], s[8:9]
	s_add_u32 s0, s12, 0xb0000
	s_addc_u32 s1, s13, 0
	global_load_dwordx4 v[156:159], v232, s[0:1] nt
	global_load_dwordx4 v[160:163], v232, s[0:1] offset:16 nt
	s_waitcnt vmcnt(12)
	v_pk_fma_f32 v[110:111], v[110:111], v[182:183], v[164:165]
	v_pk_fma_f32 v[112:113], v[112:113], v[184:185], v[166:167]
	v_pk_fma_f32 v[106:107], v[106:107], v[186:187], v[168:169]
	v_pk_fma_f32 v[108:109], v[108:109], v[188:189], v[170:171]
	v_cvt_pk_bf16_f32 v110, v110, v111
	v_cvt_pk_bf16_f32 v111, v112, v113
	v_cvt_pk_bf16_f32 v112, v106, v107
	v_cvt_pk_bf16_f32 v113, v108, v109
	s_add_u32 s8, s14, 0x10000
	s_addc_u32 s9, s15, 0
	global_store_dwordx4 v233, v[110:113], s[8:9]
	s_add_u32 s0, s12, 0x200
	s_addc_u32 s1, s13, 0
	global_load_dwordx4 v[164:167], v232, s[0:1] nt
	global_load_dwordx4 v[168:171], v232, s[0:1] offset:16 nt
	s_waitcnt vmcnt(13)
	v_pk_fma_f32 v[102:103], v[102:103], v[182:183], v[172:173]
	v_pk_fma_f32 v[104:105], v[104:105], v[184:185], v[174:175]
	v_pk_fma_f32 v[98:99], v[98:99], v[186:187], v[176:177]
	v_pk_fma_f32 v[100:101], v[100:101], v[188:189], v[178:179]
	v_cvt_pk_bf16_f32 v102, v102, v103
	v_cvt_pk_bf16_f32 v103, v104, v105
	v_cvt_pk_bf16_f32 v104, v98, v99
	v_cvt_pk_bf16_f32 v105, v100, v101
	s_add_u32 s8, s14, 0x18000
	s_addc_u32 s9, s15, 0
	global_store_dwordx4 v233, v[102:105], s[8:9]
	s_add_u32 s0, s12, 0x10200
	s_addc_u32 s1, s13, 0
	global_load_dwordx4 v[172:175], v232, s[0:1] nt
	global_load_dwordx4 v[176:179], v232, s[0:1] offset:16 nt
	s_waitcnt vmcnt(14)
	v_pk_fma_f32 v[94:95], v[94:95], v[182:183], v[198:199]
	v_pk_fma_f32 v[96:97], v[96:97], v[184:185], v[200:201]
	v_pk_fma_f32 v[90:91], v[90:91], v[186:187], v[202:203]
	v_pk_fma_f32 v[92:93], v[92:93], v[188:189], v[204:205]
	v_cvt_pk_bf16_f32 v94, v94, v95
	v_cvt_pk_bf16_f32 v95, v96, v97
	v_cvt_pk_bf16_f32 v96, v90, v91
	v_cvt_pk_bf16_f32 v97, v92, v93
	s_add_u32 s8, s14, 0x40000
	s_addc_u32 s9, s15, 0
	global_store_dwordx4 v233, v[94:97], s[8:9]
	s_add_u32 s0, s12, 0x20200
	s_addc_u32 s1, s13, 0
	global_load_dwordx4 v[198:201], v232, s[0:1] nt
	global_load_dwordx4 v[202:205], v232, s[0:1] offset:16 nt
	s_waitcnt vmcnt(15)
	v_pk_fma_f32 v[86:87], v[86:87], v[182:183], v[206:207]
	v_pk_fma_f32 v[88:89], v[88:89], v[184:185], v[208:209]
	v_pk_fma_f32 v[82:83], v[82:83], v[186:187], v[210:211]
	v_pk_fma_f32 v[84:85], v[84:85], v[188:189], v[212:213]
	v_cvt_pk_bf16_f32 v86, v86, v87
	v_cvt_pk_bf16_f32 v87, v88, v89
	v_cvt_pk_bf16_f32 v88, v82, v83
	v_cvt_pk_bf16_f32 v89, v84, v85
	s_add_u32 s8, s14, 0x48000
	s_addc_u32 s9, s15, 0
	global_store_dwordx4 v233, v[86:89], s[8:9]
	s_add_u32 s0, s12, 0x30200
	s_addc_u32 s1, s13, 0
	global_load_dwordx4 v[206:209], v232, s[0:1] nt
	global_load_dwordx4 v[210:213], v232, s[0:1] offset:16 nt
	s_waitcnt vmcnt(15)
	v_pk_fma_f32 v[78:79], v[78:79], v[182:183], v[130:131]
	v_pk_fma_f32 v[80:81], v[80:81], v[184:185], v[132:133]
	v_pk_fma_f32 v[74:75], v[74:75], v[186:187], v[134:135]
	v_pk_fma_f32 v[76:77], v[76:77], v[188:189], v[136:137]
	v_cvt_pk_bf16_f32 v78, v78, v79
	v_cvt_pk_bf16_f32 v79, v80, v81
	v_cvt_pk_bf16_f32 v80, v74, v75
	v_cvt_pk_bf16_f32 v81, v76, v77
	s_add_u32 s8, s14, 0x50000
	s_addc_u32 s9, s15, 0
	global_store_dwordx4 v233, v[78:81], s[8:9]
	s_add_u32 s0, s12, 0x80200
	s_addc_u32 s1, s13, 0
	global_load_dwordx4 v[130:133], v232, s[0:1] nt
	global_load_dwordx4 v[134:137], v232, s[0:1] offset:16 nt
	s_waitcnt vmcnt(15)
	v_pk_fma_f32 v[70:71], v[70:71], v[182:183], v[156:157]
	v_pk_fma_f32 v[72:73], v[72:73], v[184:185], v[158:159]
	v_pk_fma_f32 v[66:67], v[66:67], v[186:187], v[160:161]
	v_pk_fma_f32 v[68:69], v[68:69], v[188:189], v[162:163]
	v_cvt_pk_bf16_f32 v70, v70, v71
	v_cvt_pk_bf16_f32 v71, v72, v73
	v_cvt_pk_bf16_f32 v72, v66, v67
	v_cvt_pk_bf16_f32 v73, v68, v69
	s_add_u32 s8, s14, 0x58000
	s_addc_u32 s9, s15, 0
	global_store_dwordx4 v233, v[70:73], s[8:9]
	s_add_u32 s0, s12, 0x90200
	s_addc_u32 s1, s13, 0
	global_load_dwordx4 v[156:159], v232, s[0:1] nt
	global_load_dwordx4 v[160:163], v232, s[0:1] offset:16 nt
	s_waitcnt vmcnt(15)
	v_pk_fma_f32 v[62:63], v[62:63], v[190:191], v[164:165]
	v_pk_fma_f32 v[64:65], v[64:65], v[192:193], v[166:167]
	v_pk_fma_f32 v[58:59], v[58:59], v[194:195], v[168:169]
	v_pk_fma_f32 v[60:61], v[60:61], v[196:197], v[170:171]
	v_cvt_pk_bf16_f32 v62, v62, v63
	v_cvt_pk_bf16_f32 v63, v64, v65
	v_cvt_pk_bf16_f32 v64, v58, v59
	v_cvt_pk_bf16_f32 v65, v60, v61
	s_add_u32 s8, s14, 0x100
	s_addc_u32 s9, s15, 0
	global_store_dwordx4 v233, v[62:65], s[8:9]
	s_add_u32 s0, s12, 0xa0200
	s_addc_u32 s1, s13, 0
	global_load_dwordx4 v[164:167], v232, s[0:1] nt
	global_load_dwordx4 v[168:171], v232, s[0:1] offset:16 nt
	s_waitcnt vmcnt(15)
	v_pk_fma_f32 v[54:55], v[54:55], v[190:191], v[172:173]
	v_pk_fma_f32 v[56:57], v[56:57], v[192:193], v[174:175]
	v_pk_fma_f32 v[50:51], v[50:51], v[194:195], v[176:177]
	v_pk_fma_f32 v[52:53], v[52:53], v[196:197], v[178:179]
	v_cvt_pk_bf16_f32 v54, v54, v55
	v_cvt_pk_bf16_f32 v55, v56, v57
	v_cvt_pk_bf16_f32 v56, v50, v51
	v_cvt_pk_bf16_f32 v57, v52, v53
	s_add_u32 s8, s14, 0x8100
	s_addc_u32 s9, s15, 0
	global_store_dwordx4 v233, v[54:57], s[8:9]
	s_add_u32 s0, s12, 0xb0200
	s_addc_u32 s1, s13, 0
	global_load_dwordx4 v[172:175], v232, s[0:1] nt
	global_load_dwordx4 v[176:179], v232, s[0:1] offset:16 nt
	s_waitcnt vmcnt(15)
	v_pk_fma_f32 v[46:47], v[46:47], v[190:191], v[198:199]
	v_pk_fma_f32 v[48:49], v[48:49], v[192:193], v[200:201]
	v_pk_fma_f32 v[42:43], v[42:43], v[194:195], v[202:203]
	v_pk_fma_f32 v[44:45], v[44:45], v[196:197], v[204:205]
	v_cvt_pk_bf16_f32 v46, v46, v47
	v_cvt_pk_bf16_f32 v47, v48, v49
	v_cvt_pk_bf16_f32 v48, v42, v43
	v_cvt_pk_bf16_f32 v49, v44, v45
	s_add_u32 s8, s14, 0x10100
	s_addc_u32 s9, s15, 0
	global_store_dwordx4 v233, v[46:49], s[8:9]
	s_waitcnt vmcnt(13)
	v_pk_fma_f32 v[38:39], v[38:39], v[190:191], v[206:207]
	v_pk_fma_f32 v[40:41], v[40:41], v[192:193], v[208:209]
	v_pk_fma_f32 v[34:35], v[34:35], v[194:195], v[210:211]
	v_pk_fma_f32 v[36:37], v[36:37], v[196:197], v[212:213]
	v_cvt_pk_bf16_f32 v38, v38, v39
	v_cvt_pk_bf16_f32 v39, v40, v41
	v_cvt_pk_bf16_f32 v40, v34, v35
	v_cvt_pk_bf16_f32 v41, v36, v37
	s_add_u32 s8, s14, 0x18100
	s_addc_u32 s9, s15, 0
	global_store_dwordx4 v233, v[38:41], s[8:9]
	s_waitcnt vmcnt(11)
	v_pk_fma_f32 v[30:31], v[30:31], v[190:191], v[130:131]
	v_pk_fma_f32 v[32:33], v[32:33], v[192:193], v[132:133]
	v_pk_fma_f32 v[26:27], v[26:27], v[194:195], v[134:135]
	v_pk_fma_f32 v[28:29], v[28:29], v[196:197], v[136:137]
	v_cvt_pk_bf16_f32 v30, v30, v31
	v_cvt_pk_bf16_f32 v31, v32, v33
	v_cvt_pk_bf16_f32 v32, v26, v27
	v_cvt_pk_bf16_f32 v33, v28, v29
	s_add_u32 s8, s14, 0x40100
	s_addc_u32 s9, s15, 0
	global_store_dwordx4 v233, v[30:33], s[8:9]
	s_waitcnt vmcnt(9)
	v_pk_fma_f32 v[22:23], v[22:23], v[190:191], v[156:157]
	v_pk_fma_f32 v[24:25], v[24:25], v[192:193], v[158:159]
	v_pk_fma_f32 v[18:19], v[18:19], v[194:195], v[160:161]
	v_pk_fma_f32 v[20:21], v[20:21], v[196:197], v[162:163]
	v_cvt_pk_bf16_f32 v22, v22, v23
	v_cvt_pk_bf16_f32 v23, v24, v25
	v_cvt_pk_bf16_f32 v24, v18, v19
	v_cvt_pk_bf16_f32 v25, v20, v21
	s_add_u32 s8, s14, 0x48100
	s_addc_u32 s9, s15, 0
	global_store_dwordx4 v233, v[22:25], s[8:9]
	s_waitcnt vmcnt(7)
	v_pk_fma_f32 v[14:15], v[14:15], v[190:191], v[164:165]
	v_pk_fma_f32 v[16:17], v[16:17], v[192:193], v[166:167]
	v_pk_fma_f32 v[10:11], v[10:11], v[194:195], v[168:169]
	v_pk_fma_f32 v[12:13], v[12:13], v[196:197], v[170:171]
	v_cvt_pk_bf16_f32 v14, v14, v15
	v_cvt_pk_bf16_f32 v15, v16, v17
	v_cvt_pk_bf16_f32 v16, v10, v11
	v_cvt_pk_bf16_f32 v17, v12, v13
	s_add_u32 s8, s14, 0x50100
	s_addc_u32 s9, s15, 0
	global_store_dwordx4 v233, v[14:17], s[8:9]
	s_waitcnt vmcnt(5)
	v_pk_fma_f32 v[6:7], v[6:7], v[190:191], v[172:173]
	v_pk_fma_f32 v[8:9], v[8:9], v[192:193], v[174:175]
	v_pk_fma_f32 v[0:1], v[0:1], v[194:195], v[176:177]
	v_pk_fma_f32 v[2:3], v[2:3], v[196:197], v[178:179]
	v_cvt_pk_bf16_f32 v6, v6, v7
	v_cvt_pk_bf16_f32 v7, v8, v9
	v_cvt_pk_bf16_f32 v8, v0, v1
	v_cvt_pk_bf16_f32 v9, v2, v3
	s_add_u32 s8, s14, 0x58100
	s_addc_u32 s9, s15, 0
	global_store_dwordx4 v233, v[6:9], s[8:9]
	s_branch .Lwout_done
.Lwout_l1:
	s_lshl_b32 s0, s11, 19
	s_lshl_b32 s1, s16, 1
	s_add_u32 s0, s0, s1
	s_add_u32 s12, s30, s0
	s_addc_u32 s13, s31, 0
	s_add_u32 s0, s12, 0x0
	s_addc_u32 s1, s13, 0
	global_load_dwordx4 v[130:133], v233, s[0:1] nt
	s_add_u32 s0, s12, 0x8000
	s_addc_u32 s1, s13, 0
	global_load_dwordx4 v[134:137], v233, s[0:1] nt
	s_add_u32 s0, s12, 0x10000
	s_addc_u32 s1, s13, 0
	global_load_dwordx4 v[156:159], v233, s[0:1] nt
	s_add_u32 s0, s12, 0x18000
	s_addc_u32 s1, s13, 0
	global_load_dwordx4 v[160:163], v233, s[0:1] nt
	s_add_u32 s0, s12, 0x40000
	s_addc_u32 s1, s13, 0
	global_load_dwordx4 v[164:167], v233, s[0:1] nt
	s_add_u32 s0, s12, 0x48000
	s_addc_u32 s1, s13, 0
	global_load_dwordx4 v[168:171], v233, s[0:1] nt
	s_add_u32 s0, s12, 0x50000
	s_addc_u32 s1, s13, 0
	global_load_dwordx4 v[172:175], v233, s[0:1] nt
	s_add_u32 s0, s12, 0x58000
	s_addc_u32 s1, s13, 0
	global_load_dwordx4 v[176:179], v233, s[0:1] nt
	s_waitcnt vmcnt(7)
	v_lshlrev_b32_e32 v224, 16, v130
	v_and_b32_e32 v225, 0xffff0000, v130
	v_pk_fma_f32 v[126:127], v[126:127], v[182:183], v[224:225]
	v_lshlrev_b32_e32 v226, 16, v131
	v_and_b32_e32 v227, 0xffff0000, v131
	v_pk_fma_f32 v[128:129], v[128:129], v[184:185], v[226:227]
	v_lshlrev_b32_e32 v228, 16, v132
	v_and_b32_e32 v229, 0xffff0000, v132
	v_pk_fma_f32 v[122:123], v[122:123], v[186:187], v[228:229]
	v_lshlrev_b32_e32 v230, 16, v133
	v_and_b32_e32 v231, 0xffff0000, v133
	v_pk_fma_f32 v[124:125], v[124:125], v[188:189], v[230:231]
	v_cvt_pk_bf16_f32 v126, v126, v127
	v_cvt_pk_bf16_f32 v127, v128, v129
	v_cvt_pk_bf16_f32 v128, v122, v123
	v_cvt_pk_bf16_f32 v129, v124, v125
	s_add_u32 s8, s14, 0x0
	s_addc_u32 s9, s15, 0
	global_store_dwordx4 v233, v[126:129], s[8:9]
	s_add_u32 s0, s12, 0x100
	s_addc_u32 s1, s13, 0
	global_load_dwordx4 v[130:133], v233, s[0:1] nt
	s_waitcnt vmcnt(8)
	v_lshlrev_b32_e32 v224, 16, v134
	v_and_b32_e32 v225, 0xffff0000, v134
	v_pk_fma_f32 v[118:119], v[118:119], v[182:183], v[224:225]
	v_lshlrev_b32_e32 v226, 16, v135
	v_and_b32_e32 v227, 0xffff0000, v135
	v_pk_fma_f32 v[120:121], v[120:121], v[184:185], v[226:227]
	v_lshlrev_b32_e32 v228, 16, v136
	v_and_b32_e32 v229, 0xffff0000, v136
	v_pk_fma_f32 v[114:115], v[114:115], v[186:187], v[228:229]
	v_lshlrev_b32_e32 v230, 16, v137
	v_and_b32_e32 v231, 0xffff0000, v137
	v_pk_fma_f32 v[116:117], v[116:117], v[188:189], v[230:231]
	v_cvt_pk_bf16_f32 v118, v118, v119
	v_cvt_pk_bf16_f32 v119, v120, v121
	v_cvt_pk_bf16_f32 v120, v114, v115
	v_cvt_pk_bf16_f32 v121, v116, v117
	s_add_u32 s8, s14, 0x8000
	s_addc_u32 s9, s15, 0
	global_store_dwordx4 v233, v[118:121], s[8:9]
	s_add_u32 s0, s12, 0x8100
	s_addc_u32 s1, s13, 0
	global_load_dwordx4 v[134:137], v233, s[0:1] nt
	s_waitcnt vmcnt(9)
	v_lshlrev_b32_e32 v224, 16, v156
	v_and_b32_e32 v225, 0xffff0000, v156
	v_pk_fma_f32 v[110:111], v[110:111], v[182:183], v[224:225]
	v_lshlrev_b32_e32 v226, 16, v157
	v_and_b32_e32 v227, 0xffff0000, v157
	v_pk_fma_f32 v[112:113], v[112:113], v[184:185], v[226:227]
	v_lshlrev_b32_e32 v228, 16, v158
	v_and_b32_e32 v229, 0xffff0000, v158
	v_pk_fma_f32 v[106:107], v[106:107], v[186:187], v[228:229]
	v_lshlrev_b32_e32 v230, 16, v159
	v_and_b32_e32 v231, 0xffff0000, v159
	v_pk_fma_f32 v[108:109], v[108:109], v[188:189], v[230:231]
	v_cvt_pk_bf16_f32 v110, v110, v111
	v_cvt_pk_bf16_f32 v111, v112, v113
	v_cvt_pk_bf16_f32 v112, v106, v107
	v_cvt_pk_bf16_f32 v113, v108, v109
	s_add_u32 s8, s14, 0x10000
	s_addc_u32 s9, s15, 0
	global_store_dwordx4 v233, v[110:113], s[8:9]
	s_add_u32 s0, s12, 0x10100
	s_addc_u32 s1, s13, 0
	global_load_dwordx4 v[156:159], v233, s[0:1] nt
	s_waitcnt vmcnt(10)
	v_lshlrev_b32_e32 v224, 16, v160
	v_and_b32_e32 v225, 0xffff0000, v160
	v_pk_fma_f32 v[102:103], v[102:103], v[182:183], v[224:225]
	v_lshlrev_b32_e32 v226, 16, v161
	v_and_b32_e32 v227, 0xffff0000, v161
	v_pk_fma_f32 v[104:105], v[104:105], v[184:185], v[226:227]
	v_lshlrev_b32_e32 v228, 16, v162
	v_and_b32_e32 v229, 0xffff0000, v162
	v_pk_fma_f32 v[98:99], v[98:99], v[186:187], v[228:229]
	v_lshlrev_b32_e32 v230, 16, v163
	v_and_b32_e32 v231, 0xffff0000, v163
	v_pk_fma_f32 v[100:101], v[100:101], v[188:189], v[230:231]
	v_cvt_pk_bf16_f32 v102, v102, v103
	v_cvt_pk_bf16_f32 v103, v104, v105
	v_cvt_pk_bf16_f32 v104, v98, v99
	v_cvt_pk_bf16_f32 v105, v100, v101
	s_add_u32 s8, s14, 0x18000
	s_addc_u32 s9, s15, 0
	global_store_dwordx4 v233, v[102:105], s[8:9]
	s_add_u32 s0, s12, 0x18100
	s_addc_u32 s1, s13, 0
	global_load_dwordx4 v[160:163], v233, s[0:1] nt
	s_waitcnt vmcnt(11)
	v_lshlrev_b32_e32 v224, 16, v164
	v_and_b32_e32 v225, 0xffff0000, v164
	v_pk_fma_f32 v[94:95], v[94:95], v[182:183], v[224:225]
	v_lshlrev_b32_e32 v226, 16, v165
	v_and_b32_e32 v227, 0xffff0000, v165
	v_pk_fma_f32 v[96:97], v[96:97], v[184:185], v[226:227]
	v_lshlrev_b32_e32 v228, 16, v166
	v_and_b32_e32 v229, 0xffff0000, v166
	v_pk_fma_f32 v[90:91], v[90:91], v[186:187], v[228:229]
	v_lshlrev_b32_e32 v230, 16, v167
	v_and_b32_e32 v231, 0xffff0000, v167
	v_pk_fma_f32 v[92:93], v[92:93], v[188:189], v[230:231]
	v_cvt_pk_bf16_f32 v94, v94, v95
	v_cvt_pk_bf16_f32 v95, v96, v97
	v_cvt_pk_bf16_f32 v96, v90, v91
	v_cvt_pk_bf16_f32 v97, v92, v93
	s_add_u32 s8, s14, 0x40000
	s_addc_u32 s9, s15, 0
	global_store_dwordx4 v233, v[94:97], s[8:9]
	s_add_u32 s0, s12, 0x40100
	s_addc_u32 s1, s13, 0
	global_load_dwordx4 v[164:167], v233, s[0:1] nt
	s_waitcnt vmcnt(12)
	v_lshlrev_b32_e32 v224, 16, v168
	v_and_b32_e32 v225, 0xffff0000, v168
	v_pk_fma_f32 v[86:87], v[86:87], v[182:183], v[224:225]
	v_lshlrev_b32_e32 v226, 16, v169
	v_and_b32_e32 v227, 0xffff0000, v169
	v_pk_fma_f32 v[88:89], v[88:89], v[184:185], v[226:227]
	v_lshlrev_b32_e32 v228, 16, v170
	v_and_b32_e32 v229, 0xffff0000, v170
	v_pk_fma_f32 v[82:83], v[82:83], v[186:187], v[228:229]
	v_lshlrev_b32_e32 v230, 16, v171
	v_and_b32_e32 v231, 0xffff0000, v171
	v_pk_fma_f32 v[84:85], v[84:85], v[188:189], v[230:231]
	v_cvt_pk_bf16_f32 v86, v86, v87
	v_cvt_pk_bf16_f32 v87, v88, v89
	v_cvt_pk_bf16_f32 v88, v82, v83
	v_cvt_pk_bf16_f32 v89, v84, v85
	s_add_u32 s8, s14, 0x48000
	s_addc_u32 s9, s15, 0
	global_store_dwordx4 v233, v[86:89], s[8:9]
	s_add_u32 s0, s12, 0x48100
	s_addc_u32 s1, s13, 0
	global_load_dwordx4 v[168:171], v233, s[0:1] nt
	s_waitcnt vmcnt(13)
	v_lshlrev_b32_e32 v224, 16, v172
	v_and_b32_e32 v225, 0xffff0000, v172
	v_pk_fma_f32 v[78:79], v[78:79], v[182:183], v[224:225]
	v_lshlrev_b32_e32 v226, 16, v173
	v_and_b32_e32 v227, 0xffff0000, v173
	v_pk_fma_f32 v[80:81], v[80:81], v[184:185], v[226:227]
	v_lshlrev_b32_e32 v228, 16, v174
	v_and_b32_e32 v229, 0xffff0000, v174
	v_pk_fma_f32 v[74:75], v[74:75], v[186:187], v[228:229]
	v_lshlrev_b32_e32 v230, 16, v175
	v_and_b32_e32 v231, 0xffff0000, v175
	v_pk_fma_f32 v[76:77], v[76:77], v[188:189], v[230:231]
	v_cvt_pk_bf16_f32 v78, v78, v79
	v_cvt_pk_bf16_f32 v79, v80, v81
	v_cvt_pk_bf16_f32 v80, v74, v75
	v_cvt_pk_bf16_f32 v81, v76, v77
	s_add_u32 s8, s14, 0x50000
	s_addc_u32 s9, s15, 0
	global_store_dwordx4 v233, v[78:81], s[8:9]
	s_add_u32 s0, s12, 0x50100
	s_addc_u32 s1, s13, 0
	global_load_dwordx4 v[172:175], v233, s[0:1] nt
	s_waitcnt vmcnt(14)
	v_lshlrev_b32_e32 v224, 16, v176
	v_and_b32_e32 v225, 0xffff0000, v176
	v_pk_fma_f32 v[70:71], v[70:71], v[182:183], v[224:225]
	v_lshlrev_b32_e32 v226, 16, v177
	v_and_b32_e32 v227, 0xffff0000, v177
	v_pk_fma_f32 v[72:73], v[72:73], v[184:185], v[226:227]
	v_lshlrev_b32_e32 v228, 16, v178
	v_and_b32_e32 v229, 0xffff0000, v178
	v_pk_fma_f32 v[66:67], v[66:67], v[186:187], v[228:229]
	v_lshlrev_b32_e32 v230, 16, v179
	v_and_b32_e32 v231, 0xffff0000, v179
	v_pk_fma_f32 v[68:69], v[68:69], v[188:189], v[230:231]
	v_cvt_pk_bf16_f32 v70, v70, v71
	v_cvt_pk_bf16_f32 v71, v72, v73
	v_cvt_pk_bf16_f32 v72, v66, v67
	v_cvt_pk_bf16_f32 v73, v68, v69
	s_add_u32 s8, s14, 0x58000
	s_addc_u32 s9, s15, 0
	global_store_dwordx4 v233, v[70:73], s[8:9]
	s_add_u32 s0, s12, 0x58100
	s_addc_u32 s1, s13, 0
	global_load_dwordx4 v[176:179], v233, s[0:1] nt
	s_waitcnt vmcnt(14)
	v_lshlrev_b32_e32 v224, 16, v130
	v_and_b32_e32 v225, 0xffff0000, v130
	v_pk_fma_f32 v[62:63], v[62:63], v[190:191], v[224:225]
	v_lshlrev_b32_e32 v226, 16, v131
	v_and_b32_e32 v227, 0xffff0000, v131
	v_pk_fma_f32 v[64:65], v[64:65], v[192:193], v[226:227]
	v_lshlrev_b32_e32 v228, 16, v132
	v_and_b32_e32 v229, 0xffff0000, v132
	v_pk_fma_f32 v[58:59], v[58:59], v[194:195], v[228:229]
	v_lshlrev_b32_e32 v230, 16, v133
	v_and_b32_e32 v231, 0xffff0000, v133
	v_pk_fma_f32 v[60:61], v[60:61], v[196:197], v[230:231]
	v_cvt_pk_bf16_f32 v62, v62, v63
	v_cvt_pk_bf16_f32 v63, v64, v65
	v_cvt_pk_bf16_f32 v64, v58, v59
	v_cvt_pk_bf16_f32 v65, v60, v61
	s_add_u32 s8, s14, 0x100
	s_addc_u32 s9, s15, 0
	global_store_dwordx4 v233, v[62:65], s[8:9]
	s_waitcnt vmcnt(13)
	v_lshlrev_b32_e32 v224, 16, v134
	v_and_b32_e32 v225, 0xffff0000, v134
	v_pk_fma_f32 v[54:55], v[54:55], v[190:191], v[224:225]
	v_lshlrev_b32_e32 v226, 16, v135
	v_and_b32_e32 v227, 0xffff0000, v135
	v_pk_fma_f32 v[56:57], v[56:57], v[192:193], v[226:227]
	v_lshlrev_b32_e32 v228, 16, v136
	v_and_b32_e32 v229, 0xffff0000, v136
	v_pk_fma_f32 v[50:51], v[50:51], v[194:195], v[228:229]
	v_lshlrev_b32_e32 v230, 16, v137
	v_and_b32_e32 v231, 0xffff0000, v137
	v_pk_fma_f32 v[52:53], v[52:53], v[196:197], v[230:231]
	v_cvt_pk_bf16_f32 v54, v54, v55
	v_cvt_pk_bf16_f32 v55, v56, v57
	v_cvt_pk_bf16_f32 v56, v50, v51
	v_cvt_pk_bf16_f32 v57, v52, v53
	s_add_u32 s8, s14, 0x8100
	s_addc_u32 s9, s15, 0
	global_store_dwordx4 v233, v[54:57], s[8:9]
	s_waitcnt vmcnt(12)
	v_lshlrev_b32_e32 v224, 16, v156
	v_and_b32_e32 v225, 0xffff0000, v156
	v_pk_fma_f32 v[46:47], v[46:47], v[190:191], v[224:225]
	v_lshlrev_b32_e32 v226, 16, v157
	v_and_b32_e32 v227, 0xffff0000, v157
	v_pk_fma_f32 v[48:49], v[48:49], v[192:193], v[226:227]
	v_lshlrev_b32_e32 v228, 16, v158
	v_and_b32_e32 v229, 0xffff0000, v158
	v_pk_fma_f32 v[42:43], v[42:43], v[194:195], v[228:229]
	v_lshlrev_b32_e32 v230, 16, v159
	v_and_b32_e32 v231, 0xffff0000, v159
	v_pk_fma_f32 v[44:45], v[44:45], v[196:197], v[230:231]
	v_cvt_pk_bf16_f32 v46, v46, v47
	v_cvt_pk_bf16_f32 v47, v48, v49
	v_cvt_pk_bf16_f32 v48, v42, v43
	v_cvt_pk_bf16_f32 v49, v44, v45
	s_add_u32 s8, s14, 0x10100
	s_addc_u32 s9, s15, 0
	global_store_dwordx4 v233, v[46:49], s[8:9]
	s_waitcnt vmcnt(11)
	v_lshlrev_b32_e32 v224, 16, v160
	v_and_b32_e32 v225, 0xffff0000, v160
	v_pk_fma_f32 v[38:39], v[38:39], v[190:191], v[224:225]
	v_lshlrev_b32_e32 v226, 16, v161
	v_and_b32_e32 v227, 0xffff0000, v161
	v_pk_fma_f32 v[40:41], v[40:41], v[192:193], v[226:227]
	v_lshlrev_b32_e32 v228, 16, v162
	v_and_b32_e32 v229, 0xffff0000, v162
	v_pk_fma_f32 v[34:35], v[34:35], v[194:195], v[228:229]
	v_lshlrev_b32_e32 v230, 16, v163
	v_and_b32_e32 v231, 0xffff0000, v163
	v_pk_fma_f32 v[36:37], v[36:37], v[196:197], v[230:231]
	v_cvt_pk_bf16_f32 v38, v38, v39
	v_cvt_pk_bf16_f32 v39, v40, v41
	v_cvt_pk_bf16_f32 v40, v34, v35
	v_cvt_pk_bf16_f32 v41, v36, v37
	s_add_u32 s8, s14, 0x18100
	s_addc_u32 s9, s15, 0
	global_store_dwordx4 v233, v[38:41], s[8:9]
	s_waitcnt vmcnt(10)
	v_lshlrev_b32_e32 v224, 16, v164
	v_and_b32_e32 v225, 0xffff0000, v164
	v_pk_fma_f32 v[30:31], v[30:31], v[190:191], v[224:225]
	v_lshlrev_b32_e32 v226, 16, v165
	v_and_b32_e32 v227, 0xffff0000, v165
	v_pk_fma_f32 v[32:33], v[32:33], v[192:193], v[226:227]
	v_lshlrev_b32_e32 v228, 16, v166
	v_and_b32_e32 v229, 0xffff0000, v166
	v_pk_fma_f32 v[26:27], v[26:27], v[194:195], v[228:229]
	v_lshlrev_b32_e32 v230, 16, v167
	v_and_b32_e32 v231, 0xffff0000, v167
	v_pk_fma_f32 v[28:29], v[28:29], v[196:197], v[230:231]
	v_cvt_pk_bf16_f32 v30, v30, v31
	v_cvt_pk_bf16_f32 v31, v32, v33
	v_cvt_pk_bf16_f32 v32, v26, v27
	v_cvt_pk_bf16_f32 v33, v28, v29
	s_add_u32 s8, s14, 0x40100
	s_addc_u32 s9, s15, 0
	global_store_dwordx4 v233, v[30:33], s[8:9]
	s_waitcnt vmcnt(9)
	v_lshlrev_b32_e32 v224, 16, v168
	v_and_b32_e32 v225, 0xffff0000, v168
	v_pk_fma_f32 v[22:23], v[22:23], v[190:191], v[224:225]
	v_lshlrev_b32_e32 v226, 16, v169
	v_and_b32_e32 v227, 0xffff0000, v169
	v_pk_fma_f32 v[24:25], v[24:25], v[192:193], v[226:227]
	v_lshlrev_b32_e32 v228, 16, v170
	v_and_b32_e32 v229, 0xffff0000, v170
	v_pk_fma_f32 v[18:19], v[18:19], v[194:195], v[228:229]
	v_lshlrev_b32_e32 v230, 16, v171
	v_and_b32_e32 v231, 0xffff0000, v171
	v_pk_fma_f32 v[20:21], v[20:21], v[196:197], v[230:231]
	v_cvt_pk_bf16_f32 v22, v22, v23
	v_cvt_pk_bf16_f32 v23, v24, v25
	v_cvt_pk_bf16_f32 v24, v18, v19
	v_cvt_pk_bf16_f32 v25, v20, v21
	s_add_u32 s8, s14, 0x48100
	s_addc_u32 s9, s15, 0
	global_store_dwordx4 v233, v[22:25], s[8:9]
	s_waitcnt vmcnt(8)
	v_lshlrev_b32_e32 v224, 16, v172
	v_and_b32_e32 v225, 0xffff0000, v172
	v_pk_fma_f32 v[14:15], v[14:15], v[190:191], v[224:225]
	v_lshlrev_b32_e32 v226, 16, v173
	v_and_b32_e32 v227, 0xffff0000, v173
	v_pk_fma_f32 v[16:17], v[16:17], v[192:193], v[226:227]
	v_lshlrev_b32_e32 v228, 16, v174
	v_and_b32_e32 v229, 0xffff0000, v174
	v_pk_fma_f32 v[10:11], v[10:11], v[194:195], v[228:229]
	v_lshlrev_b32_e32 v230, 16, v175
	v_and_b32_e32 v231, 0xffff0000, v175
	v_pk_fma_f32 v[12:13], v[12:13], v[196:197], v[230:231]
	v_cvt_pk_bf16_f32 v14, v14, v15
	v_cvt_pk_bf16_f32 v15, v16, v17
	v_cvt_pk_bf16_f32 v16, v10, v11
	v_cvt_pk_bf16_f32 v17, v12, v13
	s_add_u32 s8, s14, 0x50100
	s_addc_u32 s9, s15, 0
	global_store_dwordx4 v233, v[14:17], s[8:9]
	s_waitcnt vmcnt(7)
	v_lshlrev_b32_e32 v224, 16, v176
	v_and_b32_e32 v225, 0xffff0000, v176
	v_pk_fma_f32 v[6:7], v[6:7], v[190:191], v[224:225]
	v_lshlrev_b32_e32 v226, 16, v177
	v_and_b32_e32 v227, 0xffff0000, v177
	v_pk_fma_f32 v[8:9], v[8:9], v[192:193], v[226:227]
	v_lshlrev_b32_e32 v228, 16, v178
	v_and_b32_e32 v229, 0xffff0000, v178
	v_pk_fma_f32 v[0:1], v[0:1], v[194:195], v[228:229]
	v_lshlrev_b32_e32 v230, 16, v179
	v_and_b32_e32 v231, 0xffff0000, v179
	v_pk_fma_f32 v[2:3], v[2:3], v[196:197], v[230:231]
	v_cvt_pk_bf16_f32 v6, v6, v7
	v_cvt_pk_bf16_f32 v7, v8, v9
	v_cvt_pk_bf16_f32 v8, v0, v1
	v_cvt_pk_bf16_f32 v9, v2, v3
	s_add_u32 s8, s14, 0x58100
	s_addc_u32 s9, s15, 0
	global_store_dwordx4 v233, v[6:9], s[8:9]
